# ret_out head-norm epilogue: 32 gate loads issued up front, one wait instead of 32 serialized round trips
# speedup vs baseline: 1.0068x; 1.0031x over previous
; #define LAUNDER_V(x) asm volatile("" : "+v"(x))
; __device__ __forceinline__ unsigned pk2(float lo, float hi) { return pg8::pk_bf16_rne(lo, hi); }
; __device__ __forceinline__ float bf2f(unsigned short u) { return __uint_as_float(((unsigned)u) << 16); }
; __device__ __forceinline__ float half_sum(float v) { v = row16_allsum(v); v = rows_pair_sum(v); return v; }
; __device__ __forceinline__ int crow(int r, int hi) { return (r & 3) + 8 * (r >> 2) + 4 * hi; }
; #define MFMA32(a, b, c) __builtin_amdgcn_mfma_f32_32x32x16_bf16((a), (b), (c), 0, 0, 0)
; __device__ __forceinline__ void ret_out(const Params& P, int l, unsigned char* lds, int u, int tid) {
;     ...
;     for (int dir = 0; dir < 2; ++dir) {
;         const bf16_t* Rt = RT + ((size_t)unit * 2 + dir) * 4096;
;         const float wq = dir == 0 ? __builtin_amdgcn_exp2f(lgf2 * (float)(cq + 1)) : __builtin_amdgcn_exp2f(lgb2 * (float)(128 - cq));
; #pragma unroll
;         for (int s = 0; s < 4; ++s) {
;             u32x4 w;
; #pragma unroll
;             for (int j = 0; j < 4; ++j) w[j] = pk2(bf2f((unsigned short)qr[s][2 * j]) * wq, bf2f((unsigned short)qr[s][2 * j + 1]) * wq);
;             const bf16x8 A = __builtin_bit_cast(bf16x8, w);
;             const bf16x8 b0 = *(const bf16x8*)(Rt + r32 * 64 + 16 * s + 8 * hi), b1 = *(const bf16x8*)(Rt + (32 + r32) * 64 + 16 * s + 8 * hi);
;             o0 = MFMA32(A, b0, o0); o1 = MFMA32(A, b1, o1);
;         }
;     }
;     const float g0 = gn[h * 64 + r32], g1 = gn[h * 64 + 32 + r32];
;     int c0f = c0; LAUNDER_V(c0f);
; #pragma unroll
;     for (int r = 0; r < 16; ++r) {
;         const float mean = half_sum(o0[r] + o1[r]) * (1.0f / 64.0f);
;         const float d0 = o0[r] - mean, d1 = o1[r] - mean;
;         const float var = half_sum(d0 * d0 + d1 * d1) * (1.0f / 64.0f);
;         const float rstd = 1.0f / sqrtf(var + 1e-5f);
;         const size_t t = tc + c0f + crow(r, hi);
;         const float ga = bf2f(ZR[t * 1024 + 768 + h * 64 + r32]), gb = bf2f(ZR[t * 1024 + 768 + h * 64 + 32 + r32]);
;         const float sa = ga / (1.0f + __expf(-ga)), sb = gb / (1.0f + __expf(-gb));
;         MIX[t * 1024 + 768 + h * 64 + r32] = (bf16_t)(pk2(sa * d0 * rstd * g0, 0.f) & 0xffffu);
;         MIX[t * 1024 + 768 + h * 64 + 32 + r32] = (bf16_t)(pk2(sb * d1 * rstd * g1, 0.f) & 0xffffu);
.LBB0_145:
	v_lshl_add_u64 v[50:51], s[28:29], 1, v[32:33]
	v_cndmask_b32_e64 v64, v67, v74, s[92:93]
	v_lshl_add_u64 v[88:89], v[50:51], 0, v[152:153]
	v_pk_mul_f32 v[76:77], v[64:65], v[34:35] op_sel_hi:[0,1]
	v_pk_mul_f32 v[78:79], v[64:65], v[36:37] op_sel_hi:[0,1]
	v_add_co_u32_e32 v84, vcc, s36, v88
	v_cvt_pk_bf16_f32 v76, v76, v77
	v_cvt_pk_bf16_f32 v77, v78, v79
	v_pk_mul_f32 v[78:79], v[64:65], v[38:39] op_sel_hi:[0,1]
	v_pk_mul_f32 v[80:81], v[64:65], v[40:41] op_sel_hi:[0,1]
	v_addc_co_u32_e32 v85, vcc, 0, v89, vcc
	v_cvt_pk_bf16_f32 v78, v78, v79
	v_cvt_pk_bf16_f32 v79, v80, v81
	global_load_dwordx4 v[80:83], v[88:89], off
	s_mov_b64 s[28:29], 0x1000
	global_load_dwordx4 v[84:87], v[84:85], off
	v_lshl_add_u64 v[50:51], v[88:89], 0, s[28:29]
	s_and_b64 vcc, exec, s[92:93]
	s_mov_b64 s[92:93], 0
	s_waitcnt vmcnt(1)
	v_mfma_f32_32x32x16_bf16 v[0:15], v[76:79], v[80:83], v[0:15]
	v_mul_f32_e64 v80, v64, v56
	v_mul_f32_e64 v81, v64, v57
	s_waitcnt vmcnt(0)
	v_mfma_f32_32x32x16_bf16 v[16:31], v[76:79], v[84:87], v[16:31]
	v_mul_f32_e64 v76, v64, v42
	v_mul_f32_e64 v77, v64, v43
	v_mul_f32_e64 v78, v64, v44
	v_mul_f32_e64 v79, v64, v45
	v_cvt_pk_bf16_f32 v76, v76, v77
	v_cvt_pk_bf16_f32 v77, v78, v79
	v_pk_mul_f32 v[78:79], v[64:65], v[46:47] op_sel_hi:[0,1]
	v_cvt_pk_bf16_f32 v78, v78, v79
	v_cvt_pk_bf16_f32 v79, v80, v81
	global_load_dwordx4 v[80:83], v[88:89], off offset:32
	global_load_dwordx4 v[84:87], v[50:51], off offset:32
	s_waitcnt vmcnt(1)
	v_mfma_f32_32x32x16_bf16 v[0:15], v[76:79], v[80:83], v[0:15]
	v_mul_f32_e64 v80, v64, v62
	v_mul_f32_e64 v81, v64, v63
	s_waitcnt vmcnt(0)
	v_mfma_f32_32x32x16_bf16 v[16:31], v[76:79], v[84:87], v[16:31]
	v_mul_f32_e64 v76, v64, v58
	v_mul_f32_e64 v77, v64, v59
	v_mul_f32_e64 v78, v64, v60
	v_mul_f32_e64 v79, v64, v61
	v_cvt_pk_bf16_f32 v76, v76, v77
	v_cvt_pk_bf16_f32 v77, v78, v79
	v_pk_mul_f32 v[78:79], v[64:65], v[52:53] op_sel_hi:[0,1]
	v_cvt_pk_bf16_f32 v78, v78, v79
	v_cvt_pk_bf16_f32 v79, v80, v81
	global_load_dwordx4 v[80:83], v[88:89], off offset:64
	global_load_dwordx4 v[84:87], v[50:51], off offset:64
	s_waitcnt vmcnt(1)
	v_mfma_f32_32x32x16_bf16 v[0:15], v[76:79], v[80:83], v[0:15]
	v_mul_f32_e64 v80, v64, v72
	v_mul_f32_e64 v81, v64, v73
	s_waitcnt vmcnt(0)
	v_mfma_f32_32x32x16_bf16 v[16:31], v[76:79], v[84:87], v[16:31]
	v_mul_f32_e64 v76, v64, v54
	v_mul_f32_e64 v77, v64, v55
	v_mul_f32_e64 v78, v64, v70
	v_mul_f32_e64 v79, v64, v71
	v_cvt_pk_bf16_f32 v76, v76, v77
	v_cvt_pk_bf16_f32 v77, v78, v79
	v_pk_mul_f32 v[78:79], v[64:65], v[48:49] op_sel_hi:[0,1]
	v_cvt_pk_bf16_f32 v78, v78, v79
	v_cvt_pk_bf16_f32 v79, v80, v81
	global_load_dwordx4 v[80:83], v[88:89], off offset:96
	global_load_dwordx4 v[84:87], v[50:51], off offset:96
	s_waitcnt vmcnt(1)
	v_mfma_f32_32x32x16_bf16 v[0:15], v[76:79], v[80:83], v[0:15]
	s_waitcnt vmcnt(0)
	v_mfma_f32_32x32x16_bf16 v[16:31], v[76:79], v[84:87], v[16:31]
	s_cbranch_vccnz .LBB0_145
	s_nop 10
	v_add_f32_e32 v34, v0, v16
	s_lshl_b32 s18, s88, 2
	s_add_u32 s18, s12, s18
	v_add_f32_dpp v34, v34, v34 row_ror:8 row_mask:0xf bank_mask:0xf bound_ctrl:1
	s_addc_u32 s19, s13, 0
	s_add_u32 s12, s6, 0x2c00000
	v_add_f32_dpp v34, v34, v34 row_ror:4 row_mask:0xf bank_mask:0xf bound_ctrl:1
	s_addc_u32 s13, s7, 0
	v_or_b32_e32 v36, v222, v65
	v_add_f32_dpp v34, v34, v34 row_ror:2 row_mask:0xf bank_mask:0xf bound_ctrl:1
	v_lshlrev_b32_e32 v32, 2, v36
	global_load_dword v39, v32, s[18:19]
	global_load_dword v38, v32, s[18:19] offset:128
	v_add_f32_dpp v34, v34, v34 row_ror:1 row_mask:0xf bank_mask:0xf bound_ctrl:1
	v_mov_b32_e32 v35, v34
	s_nop 1
	v_permlane16_swap_b32_e32 v34, v35
	v_add_f32_e32 v34, v34, v35
	v_fmamk_f32 v41, v34, 0xbc800000, v0
	v_fmamk_f32 v0, v34, 0xbc800000, v16
	v_mul_f32_e32 v16, v0, v0
	v_fmac_f32_e32 v16, v41, v41
	v_lshlrev_b32_e32 v152, 2, v223
	v_ashrrev_i32_e32 v67, 31, v66
	v_add_f32_dpp v16, v16, v16 row_ror:8 row_mask:0xf bank_mask:0xf bound_ctrl:1
	v_lshl_add_u64 v[32:33], v[68:69], 0, v[66:67]
	v_lshlrev_b32_e32 v126, 1, v36
	v_mov_b32_e32 v124, v152
	v_mov_b32_e32 v125, v153
	v_lshl_add_u64 v[124:125], v[32:33], 0, v[124:125]
	v_lshlrev_b64 v[124:125], 11, v[124:125]
	v_or_b32_e32 v124, v124, v126
	v_lshl_add_u64 v[124:125], s[10:11], 0, v[124:125]
	global_load_ushort v90, v[124:125], off offset:1536
	global_load_ushort v91, v[124:125], off offset:1600
	v_or_b32_e32 v124, 1, v152
	v_mov_b32_e32 v125, v153
	v_lshl_add_u64 v[124:125], v[32:33], 0, v[124:125]
	v_lshlrev_b64 v[124:125], 11, v[124:125]
	v_or_b32_e32 v124, v124, v126
	v_lshl_add_u64 v[124:125], s[10:11], 0, v[124:125]
	global_load_ushort v92, v[124:125], off offset:1536
	global_load_ushort v93, v[124:125], off offset:1600
	v_or_b32_e32 v124, 2, v152
	v_mov_b32_e32 v125, v153
	v_lshl_add_u64 v[124:125], v[32:33], 0, v[124:125]
	v_lshlrev_b64 v[124:125], 11, v[124:125]
	v_or_b32_e32 v124, v124, v126
	v_lshl_add_u64 v[124:125], s[10:11], 0, v[124:125]
	global_load_ushort v94, v[124:125], off offset:1536
	global_load_ushort v95, v[124:125], off offset:1600
	v_or_b32_e32 v124, 3, v152
	v_mov_b32_e32 v125, v153
	v_lshl_add_u64 v[124:125], v[32:33], 0, v[124:125]
	v_lshlrev_b64 v[124:125], 11, v[124:125]
	v_or_b32_e32 v124, v124, v126
	v_lshl_add_u64 v[124:125], s[10:11], 0, v[124:125]
	global_load_ushort v96, v[124:125], off offset:1536
	global_load_ushort v97, v[124:125], off offset:1600
	v_or_b32_e32 v124, 8, v152
	v_mov_b32_e32 v125, v153
	v_lshl_add_u64 v[124:125], v[32:33], 0, v[124:125]
	v_lshlrev_b64 v[124:125], 11, v[124:125]
	v_or_b32_e32 v124, v124, v126
	v_lshl_add_u64 v[124:125], s[10:11], 0, v[124:125]
	global_load_ushort v98, v[124:125], off offset:1536
; #define LAUNDER_V(x) asm volatile("" : "+v"(x))
; __device__ __forceinline__ unsigned pk2(float lo, float hi) { return pg8::pk_bf16_rne(lo, hi); }
; __device__ __forceinline__ float bf2f(unsigned short u) { return __uint_as_float(((unsigned)u) << 16); }
; __device__ __forceinline__ float half_sum(float v) { v = row16_allsum(v); v = rows_pair_sum(v); return v; }
; __device__ __forceinline__ int crow(int r, int hi) { return (r & 3) + 8 * (r >> 2) + 4 * hi; }
; __device__ __forceinline__ void ret_out(const Params& P, int l, unsigned char* lds, int u, int tid) {
;     ...
;     const float g0 = gn[h * 64 + r32], g1 = gn[h * 64 + 32 + r32];
;     int c0f = c0; LAUNDER_V(c0f);
; #pragma unroll
;     for (int r = 0; r < 16; ++r) {
;         const float mean = half_sum(o0[r] + o1[r]) * (1.0f / 64.0f);
;         const float d0 = o0[r] - mean, d1 = o1[r] - mean;
;         const float var = half_sum(d0 * d0 + d1 * d1) * (1.0f / 64.0f);
;         const float rstd = 1.0f / sqrtf(var + 1e-5f);
;         const size_t t = tc + c0f + crow(r, hi);
;         const float ga = bf2f(ZR[t * 1024 + 768 + h * 64 + r32]), gb = bf2f(ZR[t * 1024 + 768 + h * 64 + 32 + r32]);
;         const float sa = ga / (1.0f + __expf(-ga)), sb = gb / (1.0f + __expf(-gb));
;         MIX[t * 1024 + 768 + h * 64 + r32] = (bf16_t)(pk2(sa * d0 * rstd * g0, 0.f) & 0xffffu);
;         MIX[t * 1024 + 768 + h * 64 + 32 + r32] = (bf16_t)(pk2(sb * d1 * rstd * g1, 0.f) & 0xffffu);
	global_load_ushort v99, v[124:125], off offset:1600
	v_or_b32_e32 v124, 9, v152
	v_mov_b32_e32 v125, v153
	v_lshl_add_u64 v[124:125], v[32:33], 0, v[124:125]
	v_lshlrev_b64 v[124:125], 11, v[124:125]
	v_or_b32_e32 v124, v124, v126
	v_lshl_add_u64 v[124:125], s[10:11], 0, v[124:125]
	global_load_ushort v100, v[124:125], off offset:1536
	global_load_ushort v101, v[124:125], off offset:1600
	v_or_b32_e32 v124, 10, v152
	v_mov_b32_e32 v125, v153
	v_lshl_add_u64 v[124:125], v[32:33], 0, v[124:125]
	v_lshlrev_b64 v[124:125], 11, v[124:125]
	v_or_b32_e32 v124, v124, v126
	v_lshl_add_u64 v[124:125], s[10:11], 0, v[124:125]
	global_load_ushort v102, v[124:125], off offset:1536
	global_load_ushort v103, v[124:125], off offset:1600
	v_or_b32_e32 v124, 11, v152
	v_mov_b32_e32 v125, v153
	v_lshl_add_u64 v[124:125], v[32:33], 0, v[124:125]
	v_lshlrev_b64 v[124:125], 11, v[124:125]
	v_or_b32_e32 v124, v124, v126
	v_lshl_add_u64 v[124:125], s[10:11], 0, v[124:125]
	global_load_ushort v104, v[124:125], off offset:1536
	global_load_ushort v105, v[124:125], off offset:1600
	v_or_b32_e32 v124, 16, v152
	v_mov_b32_e32 v125, v153
	v_lshl_add_u64 v[124:125], v[32:33], 0, v[124:125]
	v_lshlrev_b64 v[124:125], 11, v[124:125]
	v_or_b32_e32 v124, v124, v126
	v_lshl_add_u64 v[124:125], s[10:11], 0, v[124:125]
	global_load_ushort v106, v[124:125], off offset:1536
	global_load_ushort v107, v[124:125], off offset:1600
	v_or_b32_e32 v124, 17, v152
	v_mov_b32_e32 v125, v153
	v_lshl_add_u64 v[124:125], v[32:33], 0, v[124:125]
	v_lshlrev_b64 v[124:125], 11, v[124:125]
	v_or_b32_e32 v124, v124, v126
	v_lshl_add_u64 v[124:125], s[10:11], 0, v[124:125]
	global_load_ushort v108, v[124:125], off offset:1536
	global_load_ushort v109, v[124:125], off offset:1600
	v_or_b32_e32 v124, 18, v152
	v_mov_b32_e32 v125, v153
	v_lshl_add_u64 v[124:125], v[32:33], 0, v[124:125]
	v_lshlrev_b64 v[124:125], 11, v[124:125]
	v_or_b32_e32 v124, v124, v126
	v_lshl_add_u64 v[124:125], s[10:11], 0, v[124:125]
	global_load_ushort v110, v[124:125], off offset:1536
	global_load_ushort v111, v[124:125], off offset:1600
	v_or_b32_e32 v124, 19, v152
	v_mov_b32_e32 v125, v153
	v_lshl_add_u64 v[124:125], v[32:33], 0, v[124:125]
	v_lshlrev_b64 v[124:125], 11, v[124:125]
	v_or_b32_e32 v124, v124, v126
	v_lshl_add_u64 v[124:125], s[10:11], 0, v[124:125]
	global_load_ushort v112, v[124:125], off offset:1536
	global_load_ushort v113, v[124:125], off offset:1600
	v_or_b32_e32 v124, 24, v152
	v_mov_b32_e32 v125, v153
	v_lshl_add_u64 v[124:125], v[32:33], 0, v[124:125]
	v_lshlrev_b64 v[124:125], 11, v[124:125]
	v_or_b32_e32 v124, v124, v126
	v_lshl_add_u64 v[124:125], s[10:11], 0, v[124:125]
	global_load_ushort v114, v[124:125], off offset:1536
	global_load_ushort v115, v[124:125], off offset:1600
	v_or_b32_e32 v124, 25, v152
	v_mov_b32_e32 v125, v153
	v_lshl_add_u64 v[124:125], v[32:33], 0, v[124:125]
	v_lshlrev_b64 v[124:125], 11, v[124:125]
	v_or_b32_e32 v124, v124, v126
	v_lshl_add_u64 v[124:125], s[10:11], 0, v[124:125]
	global_load_ushort v116, v[124:125], off offset:1536
	global_load_ushort v117, v[124:125], off offset:1600
	v_or_b32_e32 v124, 26, v152
	v_mov_b32_e32 v125, v153
	v_lshl_add_u64 v[124:125], v[32:33], 0, v[124:125]
	v_lshlrev_b64 v[124:125], 11, v[124:125]
	v_or_b32_e32 v124, v124, v126
	v_lshl_add_u64 v[124:125], s[10:11], 0, v[124:125]
	global_load_ushort v118, v[124:125], off offset:1536
	global_load_ushort v119, v[124:125], off offset:1600
	v_or_b32_e32 v124, 27, v152
	v_mov_b32_e32 v125, v153
	v_lshl_add_u64 v[124:125], v[32:33], 0, v[124:125]
	v_lshlrev_b64 v[124:125], 11, v[124:125]
	v_or_b32_e32 v124, v124, v126
	v_lshl_add_u64 v[124:125], s[10:11], 0, v[124:125]
	global_load_ushort v120, v[124:125], off offset:1536
	global_load_ushort v121, v[124:125], off offset:1600
	s_nop 0
	v_add_f32_dpp v16, v16, v16 row_ror:4 row_mask:0xf bank_mask:0xf bound_ctrl:1
	s_nop 1
	v_add_f32_dpp v16, v16, v16 row_ror:2 row_mask:0xf bank_mask:0xf bound_ctrl:1
	s_nop 1
	v_add_f32_dpp v16, v16, v16 row_ror:1 row_mask:0xf bank_mask:0xf bound_ctrl:1
	v_mov_b32_e32 v34, v16
	s_nop 1
	v_permlane16_swap_b32_e32 v16, v34
	v_add_f32_e32 v16, v16, v34
	v_fmamk_f32 v16, v16, 0x3c800000, v200
	v_cmp_gt_f32_e32 vcc, s43, v16
	v_mul_f32_e32 v34, 0x4f800000, v16
	s_nop 0
	v_cndmask_b32_e32 v16, v16, v34, vcc
	v_sqrt_f32_e32 v34, v16
	s_nop 0
	v_add_u32_e32 v35, -1, v34
	v_fma_f32 v37, -v35, v34, v16
	v_cmp_ge_f32_e64 s[6:7], 0, v37
	v_add_u32_e32 v37, 1, v34
	s_nop 0
	v_cndmask_b32_e64 v35, v34, v35, s[6:7]
	v_fma_f32 v34, -v37, v34, v16
	v_cmp_lt_f32_e64 s[6:7], 0, v34
	s_nop 1
	v_cndmask_b32_e64 v34, v35, v37, s[6:7]
	v_mul_f32_e32 v35, 0x37800000, v34
	v_cndmask_b32_e32 v34, v34, v35, vcc
	v_cmp_class_f32_e32 vcc, v16, v175
	s_nop 1
	v_cndmask_b32_e32 v16, v34, v16, vcc
	v_div_scale_f32 v34, s[6:7], v16, v16, 1.0
	v_rcp_f32_e32 v35, v34
	s_nop 0
	v_fma_f32 v37, -v34, v35, 1.0
	v_fmac_f32_e32 v35, v37, v35
	v_div_scale_f32 v37, vcc, 1.0, v16, 1.0
	v_mul_f32_e32 v40, v37, v35
	v_fma_f32 v42, -v34, v40, v37
	v_fmac_f32_e32 v40, v42, v35
	v_fma_f32 v34, -v34, v40, v37
	v_div_fmas_f32 v34, v34, v35, v40
	v_div_fixup_f32 v16, v34, v16, 1.0
	v_lshl_add_u64 v[34:35], v[32:33], 0, v[152:153]
	v_lshlrev_b64 v[34:35], 11, v[34:35]
	v_lshlrev_b32_e32 v40, 1, v36
	v_or_b32_e32 v42, v34, v40
	v_or_b32_e32 v34, 0x600, v42
	v_lshl_add_u64 v[36:37], s[10:11], 0, v[34:35]
	s_nop 0
	v_mov_b32_e32 v37, v35
	v_lshl_add_u64 v[34:35], s[12:13], 0, v[34:35]
	s_waitcnt vmcnt(0)
; __device__ __forceinline__ unsigned pk2(float lo, float hi) { return pg8::pk_bf16_rne(lo, hi); }
; __device__ __forceinline__ float bf2f(unsigned short u) { return __uint_as_float(((unsigned)u) << 16); }
; __device__ __forceinline__ float half_sum(float v) { v = row16_allsum(v); v = rows_pair_sum(v); return v; }
; __device__ __forceinline__ int crow(int r, int hi) { return (r & 3) + 8 * (r >> 2) + 4 * hi; }
; __device__ __forceinline__ void ret_out(const Params& P, int l, unsigned char* lds, int u, int tid) {
;     ...
;     for (int r = 0; r < 16; ++r) {
;         const float mean = half_sum(o0[r] + o1[r]) * (1.0f / 64.0f);
;         const float d0 = o0[r] - mean, d1 = o1[r] - mean;
;         const float var = half_sum(d0 * d0 + d1 * d1) * (1.0f / 64.0f);
;         const float rstd = 1.0f / sqrtf(var + 1e-5f);
;         const size_t t = tc + c0f + crow(r, hi);
;         const float ga = bf2f(ZR[t * 1024 + 768 + h * 64 + r32]), gb = bf2f(ZR[t * 1024 + 768 + h * 64 + 32 + r32]);
;         const float sa = ga / (1.0f + __expf(-ga)), sb = gb / (1.0f + __expf(-gb));
;         MIX[t * 1024 + 768 + h * 64 + r32] = (bf16_t)(pk2(sa * d0 * rstd * g0, 0.f) & 0xffffu);
;         MIX[t * 1024 + 768 + h * 64 + 32 + r32] = (bf16_t)(pk2(sb * d1 * rstd * g1, 0.f) & 0xffffu);
	v_lshlrev_b32_e32 v44, 16, v90
	v_or_b32_e32 v36, 0x640, v42
	v_lshl_add_u64 v[42:43], s[10:11], 0, v[36:37]
	s_nop 0
	v_mul_f32_e32 v43, 0xbfb8aa3b, v44
	v_exp_f32_e32 v43, v43
	v_lshlrev_b32_e32 v42, 16, v91
	v_add_f32_e32 v43, 1.0, v43
	v_div_scale_f32 v45, s[6:7], v43, v43, v44
	v_rcp_f32_e32 v46, v45
	s_nop 0
	v_fma_f32 v47, -v45, v46, 1.0
	v_fmac_f32_e32 v46, v47, v46
	v_div_scale_f32 v47, vcc, v44, v43, v44
	v_mul_f32_e32 v48, v47, v46
	v_fma_f32 v49, -v45, v48, v47
	v_fmac_f32_e32 v48, v49, v46
	v_fma_f32 v45, -v45, v48, v47
	v_div_fmas_f32 v45, v45, v46, v48
	v_div_fixup_f32 v43, v45, v43, v44
	v_mul_f32_e32 v44, 0xbfb8aa3b, v42
	v_exp_f32_e32 v44, v44
	v_mul_f32_e32 v41, v41, v43
	v_mul_f32_e32 v41, v16, v41
	v_mul_f32_e32 v41, v39, v41
	v_add_f32_e32 v44, 1.0, v44
	v_div_scale_f32 v45, s[6:7], v44, v44, v42
	v_rcp_f32_e32 v46, v45
	v_cvt_pk_bf16_f32 v41, v41, s0
	global_store_short v[34:35], v41, off
	v_lshl_add_u64 v[34:35], s[12:13], 0, v[36:37]
	v_fma_f32 v47, -v45, v46, 1.0
	v_fmac_f32_e32 v46, v47, v46
	v_div_scale_f32 v47, vcc, v42, v44, v42
	v_mul_f32_e32 v48, v47, v46
	v_fma_f32 v49, -v45, v48, v47
	v_fmac_f32_e32 v48, v49, v46
	v_fma_f32 v45, -v45, v48, v47
	v_div_fmas_f32 v45, v45, v46, v48
	v_div_fixup_f32 v42, v45, v44, v42
	v_mul_f32_e32 v0, v0, v42
	v_mul_f32_e32 v0, v16, v0
	v_mul_f32_e32 v0, v38, v0
	v_cvt_pk_bf16_f32 v0, v0, s0
	global_store_short v[34:35], v0, off
	v_add_f32_e32 v0, v1, v17
	s_nop 1
	v_add_f32_dpp v0, v0, v0 row_ror:8 row_mask:0xf bank_mask:0xf bound_ctrl:1
	s_nop 1
	v_add_f32_dpp v0, v0, v0 row_ror:4 row_mask:0xf bank_mask:0xf bound_ctrl:1
	s_nop 1
	v_add_f32_dpp v0, v0, v0 row_ror:2 row_mask:0xf bank_mask:0xf bound_ctrl:1
	s_nop 1
	v_add_f32_dpp v0, v0, v0 row_ror:1 row_mask:0xf bank_mask:0xf bound_ctrl:1
	v_mov_b32_e32 v16, v0
	s_nop 1
	v_permlane16_swap_b32_e32 v0, v16
	v_add_f32_e32 v0, v0, v16
	v_fmamk_f32 v34, v0, 0xbc800000, v17
	v_fmamk_f32 v35, v0, 0xbc800000, v1
	v_mul_f32_e32 v0, v34, v34
	v_fmac_f32_e32 v0, v35, v35
	s_nop 1
	v_add_f32_dpp v0, v0, v0 row_ror:8 row_mask:0xf bank_mask:0xf bound_ctrl:1
	s_nop 1
	v_add_f32_dpp v0, v0, v0 row_ror:4 row_mask:0xf bank_mask:0xf bound_ctrl:1
	s_nop 1
	v_add_f32_dpp v0, v0, v0 row_ror:2 row_mask:0xf bank_mask:0xf bound_ctrl:1
	s_nop 1
	v_add_f32_dpp v0, v0, v0 row_ror:1 row_mask:0xf bank_mask:0xf bound_ctrl:1
	v_mov_b32_e32 v1, v0
	s_nop 1
	v_permlane16_swap_b32_e32 v0, v1
	v_add_f32_e32 v0, v0, v1
	v_fmamk_f32 v0, v0, 0x3c800000, v200
	v_cmp_gt_f32_e32 vcc, s43, v0
	v_mul_f32_e32 v1, 0x4f800000, v0
	s_nop 0
	v_cndmask_b32_e32 v0, v0, v1, vcc
	v_sqrt_f32_e32 v1, v0
	s_nop 0
	v_add_u32_e32 v16, -1, v1
	v_fma_f32 v17, -v16, v1, v0
	v_cmp_ge_f32_e64 s[6:7], 0, v17
	v_add_u32_e32 v17, 1, v1
	s_nop 0
	v_cndmask_b32_e64 v16, v1, v16, s[6:7]
	v_fma_f32 v1, -v17, v1, v0
	v_cmp_lt_f32_e64 s[6:7], 0, v1
	s_nop 1
	v_cndmask_b32_e64 v1, v16, v17, s[6:7]
	v_mul_f32_e32 v16, 0x37800000, v1
	v_cndmask_b32_e32 v1, v1, v16, vcc
	v_cmp_class_f32_e32 vcc, v0, v175
	s_nop 1
	v_cndmask_b32_e32 v0, v1, v0, vcc
	v_div_scale_f32 v1, s[6:7], v0, v0, 1.0
	v_rcp_f32_e32 v16, v1
	s_nop 0
	v_fma_f32 v17, -v1, v16, 1.0
	v_fmac_f32_e32 v16, v17, v16
	v_div_scale_f32 v17, vcc, 1.0, v0, 1.0
	v_mul_f32_e32 v36, v17, v16
	v_fma_f32 v37, -v1, v36, v17
	v_fmac_f32_e32 v36, v37, v16
	v_fma_f32 v1, -v1, v36, v17
	v_div_fmas_f32 v1, v1, v16, v36
	v_div_fixup_f32 v36, v1, v0, 1.0
	v_or_b32_e32 v0, 1, v152
	v_mov_b32_e32 v1, v153
	v_lshl_add_u64 v[0:1], v[32:33], 0, v[0:1]
	v_lshlrev_b64 v[0:1], 11, v[0:1]
	v_or_b32_e32 v37, v0, v40
	v_or_b32_e32 v0, 0x600, v37
	v_lshl_add_u64 v[16:17], s[10:11], 0, v[0:1]
	s_nop 0
	v_mov_b32_e32 v17, v1
	v_lshl_add_u64 v[0:1], s[12:13], 0, v[0:1]
	v_lshlrev_b32_e32 v41, 16, v92
	v_or_b32_e32 v16, 0x640, v37
	v_lshl_add_u64 v[42:43], s[10:11], 0, v[16:17]
	s_nop 0
	v_mul_f32_e32 v42, 0xbfb8aa3b, v41
	v_exp_f32_e32 v42, v42
	v_lshlrev_b32_e32 v37, 16, v93
	v_add_f32_e32 v42, 1.0, v42
	v_div_scale_f32 v43, s[6:7], v42, v42, v41
	v_rcp_f32_e32 v44, v43
	s_nop 0
	v_fma_f32 v45, -v43, v44, 1.0
	v_fmac_f32_e32 v44, v45, v44
	v_div_scale_f32 v45, vcc, v41, v42, v41
	v_mul_f32_e32 v46, v45, v44
	v_fma_f32 v47, -v43, v46, v45
	v_fmac_f32_e32 v46, v47, v44
	v_fma_f32 v43, -v43, v46, v45
	v_div_fmas_f32 v43, v43, v44, v46
	v_div_fixup_f32 v41, v43, v42, v41
	v_mul_f32_e32 v42, 0xbfb8aa3b, v37
	v_exp_f32_e32 v42, v42
	v_mul_f32_e32 v35, v35, v41
	v_mul_f32_e32 v35, v36, v35
	v_mul_f32_e32 v35, v39, v35
	v_add_f32_e32 v42, 1.0, v42
	v_div_scale_f32 v43, s[6:7], v42, v42, v37
	v_rcp_f32_e32 v44, v43
	v_cvt_pk_bf16_f32 v35, v35, s0
	global_store_short v[0:1], v35, off
	v_fma_f32 v45, -v43, v44, 1.0
	v_fmac_f32_e32 v44, v45, v44
	v_div_scale_f32 v45, vcc, v37, v42, v37
	v_mul_f32_e32 v46, v45, v44
	v_fma_f32 v47, -v43, v46, v45
	v_fmac_f32_e32 v46, v47, v44
	v_fma_f32 v43, -v43, v46, v45
	v_div_fmas_f32 v43, v43, v44, v46
	v_div_fixup_f32 v37, v43, v42, v37
	v_mul_f32_e32 v0, v34, v37
	v_mul_f32_e32 v0, v36, v0
	v_mul_f32_e32 v0, v38, v0
	v_cvt_pk_bf16_f32 v34, v0, s0
	v_lshl_add_u64 v[0:1], s[12:13], 0, v[16:17]
	global_store_short v[0:1], v34, off
	v_add_f32_e32 v0, v2, v18
	s_nop 1
	v_add_f32_dpp v0, v0, v0 row_ror:8 row_mask:0xf bank_mask:0xf bound_ctrl:1
	s_nop 1
	v_add_f32_dpp v0, v0, v0 row_ror:4 row_mask:0xf bank_mask:0xf bound_ctrl:1
	s_nop 1
	v_add_f32_dpp v0, v0, v0 row_ror:2 row_mask:0xf bank_mask:0xf bound_ctrl:1
	s_nop 1
	v_add_f32_dpp v0, v0, v0 row_ror:1 row_mask:0xf bank_mask:0xf bound_ctrl:1
	v_mov_b32_e32 v1, v0
	s_nop 1
	v_permlane16_swap_b32_e32 v0, v1
	v_add_f32_e32 v0, v0, v1
	v_fmamk_f32 v34, v0, 0xbc800000, v2
	v_fmamk_f32 v2, v0, 0xbc800000, v18
; __device__ __forceinline__ unsigned pk2(float lo, float hi) { return pg8::pk_bf16_rne(lo, hi); }
; __device__ __forceinline__ float bf2f(unsigned short u) { return __uint_as_float(((unsigned)u) << 16); }
; __device__ __forceinline__ float half_sum(float v) { v = row16_allsum(v); v = rows_pair_sum(v); return v; }
; __device__ __forceinline__ int crow(int r, int hi) { return (r & 3) + 8 * (r >> 2) + 4 * hi; }
; __device__ __forceinline__ void ret_out(const Params& P, int l, unsigned char* lds, int u, int tid) {
;     ...
;     for (int r = 0; r < 16; ++r) {
;         const float mean = half_sum(o0[r] + o1[r]) * (1.0f / 64.0f);
;         const float d0 = o0[r] - mean, d1 = o1[r] - mean;
;         const float var = half_sum(d0 * d0 + d1 * d1) * (1.0f / 64.0f);
;         const float rstd = 1.0f / sqrtf(var + 1e-5f);
;         const size_t t = tc + c0f + crow(r, hi);
;         const float ga = bf2f(ZR[t * 1024 + 768 + h * 64 + r32]), gb = bf2f(ZR[t * 1024 + 768 + h * 64 + 32 + r32]);
;         const float sa = ga / (1.0f + __expf(-ga)), sb = gb / (1.0f + __expf(-gb));
;         MIX[t * 1024 + 768 + h * 64 + r32] = (bf16_t)(pk2(sa * d0 * rstd * g0, 0.f) & 0xffffu);
;         MIX[t * 1024 + 768 + h * 64 + 32 + r32] = (bf16_t)(pk2(sb * d1 * rstd * g1, 0.f) & 0xffffu);
	v_mul_f32_e32 v0, v2, v2
	v_fmac_f32_e32 v0, v34, v34
	s_nop 1
	v_add_f32_dpp v0, v0, v0 row_ror:8 row_mask:0xf bank_mask:0xf bound_ctrl:1
	s_nop 1
	v_add_f32_dpp v0, v0, v0 row_ror:4 row_mask:0xf bank_mask:0xf bound_ctrl:1
	s_nop 1
	v_add_f32_dpp v0, v0, v0 row_ror:2 row_mask:0xf bank_mask:0xf bound_ctrl:1
	s_nop 1
	v_add_f32_dpp v0, v0, v0 row_ror:1 row_mask:0xf bank_mask:0xf bound_ctrl:1
	v_mov_b32_e32 v1, v0
	s_nop 1
	v_permlane16_swap_b32_e32 v0, v1
	v_add_f32_e32 v0, v0, v1
	v_fmamk_f32 v0, v0, 0x3c800000, v200
	v_cmp_gt_f32_e32 vcc, s43, v0
	v_mul_f32_e32 v1, 0x4f800000, v0
	s_nop 0
	v_cndmask_b32_e32 v0, v0, v1, vcc
	v_sqrt_f32_e32 v1, v0
	s_nop 0
	v_add_u32_e32 v16, -1, v1
	v_fma_f32 v17, -v16, v1, v0
	v_cmp_ge_f32_e64 s[6:7], 0, v17
	v_add_u32_e32 v17, 1, v1
	s_nop 0
	v_cndmask_b32_e64 v16, v1, v16, s[6:7]
	v_fma_f32 v1, -v17, v1, v0
	v_cmp_lt_f32_e64 s[6:7], 0, v1
	s_nop 1
	v_cndmask_b32_e64 v1, v16, v17, s[6:7]
	v_mul_f32_e32 v16, 0x37800000, v1
	v_cndmask_b32_e32 v1, v1, v16, vcc
	v_cmp_class_f32_e32 vcc, v0, v175
	s_nop 1
	v_cndmask_b32_e32 v0, v1, v0, vcc
	v_div_scale_f32 v1, s[6:7], v0, v0, 1.0
	v_rcp_f32_e32 v16, v1
	s_nop 0
	v_fma_f32 v17, -v1, v16, 1.0
	v_fmac_f32_e32 v16, v17, v16
	v_div_scale_f32 v17, vcc, 1.0, v0, 1.0
	v_mul_f32_e32 v18, v17, v16
	v_fma_f32 v35, -v1, v18, v17
	v_fmac_f32_e32 v18, v35, v16
	v_fma_f32 v1, -v1, v18, v17
	v_div_fmas_f32 v1, v1, v16, v18
	v_div_fixup_f32 v18, v1, v0, 1.0
	v_or_b32_e32 v0, 2, v152
	v_mov_b32_e32 v1, v153
	v_lshl_add_u64 v[0:1], v[32:33], 0, v[0:1]
	v_lshlrev_b64 v[0:1], 11, v[0:1]
	v_or_b32_e32 v35, v0, v40
	v_or_b32_e32 v0, 0x600, v35
	v_lshl_add_u64 v[16:17], s[10:11], 0, v[0:1]
	s_nop 0
	v_mov_b32_e32 v17, v1
	v_lshl_add_u64 v[0:1], s[12:13], 0, v[0:1]
	v_lshlrev_b32_e32 v41, 16, v94
	v_or_b32_e32 v16, 0x640, v35
	v_lshl_add_u64 v[36:37], s[10:11], 0, v[16:17]
	s_nop 0
	v_mul_f32_e32 v36, 0xbfb8aa3b, v41
	v_exp_f32_e32 v36, v36
	v_lshlrev_b32_e32 v35, 16, v95
	v_add_f32_e32 v36, 1.0, v36
	v_div_scale_f32 v37, s[6:7], v36, v36, v41
	v_rcp_f32_e32 v42, v37
	s_nop 0
	v_fma_f32 v43, -v37, v42, 1.0
	v_fmac_f32_e32 v42, v43, v42
	v_div_scale_f32 v43, vcc, v41, v36, v41
	v_mul_f32_e32 v44, v43, v42
	v_fma_f32 v45, -v37, v44, v43
	v_fmac_f32_e32 v44, v45, v42
	v_fma_f32 v37, -v37, v44, v43
	v_div_fmas_f32 v37, v37, v42, v44
	v_div_fixup_f32 v36, v37, v36, v41
	v_mul_f32_e32 v37, 0xbfb8aa3b, v35
	v_exp_f32_e32 v37, v37
	v_mul_f32_e32 v34, v34, v36
	v_mul_f32_e32 v34, v18, v34
	v_mul_f32_e32 v34, v39, v34
	v_add_f32_e32 v37, 1.0, v37
	v_div_scale_f32 v41, s[6:7], v37, v37, v35
	v_rcp_f32_e32 v42, v41
	v_cvt_pk_bf16_f32 v34, v34, s0
	global_store_short v[0:1], v34, off
	v_fma_f32 v43, -v41, v42, 1.0
	v_fmac_f32_e32 v42, v43, v42
	v_div_scale_f32 v43, vcc, v35, v37, v35
	v_mul_f32_e32 v44, v43, v42
	v_fma_f32 v45, -v41, v44, v43
	v_fmac_f32_e32 v44, v45, v42
	v_fma_f32 v41, -v41, v44, v43
	v_div_fmas_f32 v41, v41, v42, v44
	v_div_fixup_f32 v35, v41, v37, v35
	v_mul_f32_e32 v0, v2, v35
	v_mul_f32_e32 v0, v18, v0
	v_mul_f32_e32 v0, v38, v0
	v_cvt_pk_bf16_f32 v2, v0, s0
	v_lshl_add_u64 v[0:1], s[12:13], 0, v[16:17]
	global_store_short v[0:1], v2, off
	v_add_f32_e32 v0, v3, v19
	s_nop 1
	v_add_f32_dpp v0, v0, v0 row_ror:8 row_mask:0xf bank_mask:0xf bound_ctrl:1
	s_nop 1
	v_add_f32_dpp v0, v0, v0 row_ror:4 row_mask:0xf bank_mask:0xf bound_ctrl:1
	s_nop 1
	v_add_f32_dpp v0, v0, v0 row_ror:2 row_mask:0xf bank_mask:0xf bound_ctrl:1
	s_nop 1
	v_add_f32_dpp v0, v0, v0 row_ror:1 row_mask:0xf bank_mask:0xf bound_ctrl:1
	v_mov_b32_e32 v1, v0
	s_nop 1
	v_permlane16_swap_b32_e32 v0, v1
	v_add_f32_e32 v0, v0, v1
	v_fmamk_f32 v16, v0, 0xbc800000, v19
	v_fmamk_f32 v17, v0, 0xbc800000, v3
	v_mul_f32_e32 v0, v16, v16
	v_fmac_f32_e32 v0, v17, v17
	s_nop 1
	v_add_f32_dpp v0, v0, v0 row_ror:8 row_mask:0xf bank_mask:0xf bound_ctrl:1
	s_nop 1
	v_add_f32_dpp v0, v0, v0 row_ror:4 row_mask:0xf bank_mask:0xf bound_ctrl:1
	s_nop 1
	v_add_f32_dpp v0, v0, v0 row_ror:2 row_mask:0xf bank_mask:0xf bound_ctrl:1
	s_nop 1
	v_add_f32_dpp v0, v0, v0 row_ror:1 row_mask:0xf bank_mask:0xf bound_ctrl:1
	v_mov_b32_e32 v1, v0
	s_nop 1
	v_permlane16_swap_b32_e32 v0, v1
	v_add_f32_e32 v0, v0, v1
	v_fmamk_f32 v0, v0, 0x3c800000, v200
	v_cmp_gt_f32_e32 vcc, s43, v0
	v_mul_f32_e32 v1, 0x4f800000, v0
	s_nop 0
	v_cndmask_b32_e32 v0, v0, v1, vcc
	v_sqrt_f32_e32 v1, v0
	s_nop 0
	v_add_u32_e32 v2, -1, v1
	v_fma_f32 v3, -v2, v1, v0
	v_cmp_ge_f32_e64 s[6:7], 0, v3
	v_add_u32_e32 v3, 1, v1
	s_nop 0
	v_cndmask_b32_e64 v2, v1, v2, s[6:7]
	v_fma_f32 v1, -v3, v1, v0
	v_cmp_lt_f32_e64 s[6:7], 0, v1
	s_nop 1
	v_cndmask_b32_e64 v1, v2, v3, s[6:7]
	v_mul_f32_e32 v2, 0x37800000, v1
	v_cndmask_b32_e32 v1, v1, v2, vcc
	v_cmp_class_f32_e32 vcc, v0, v175
	s_nop 1
	v_cndmask_b32_e32 v0, v1, v0, vcc
	v_div_scale_f32 v1, s[6:7], v0, v0, 1.0
	v_rcp_f32_e32 v2, v1
	s_nop 0
	v_fma_f32 v3, -v1, v2, 1.0
	v_fmac_f32_e32 v2, v3, v2
	v_div_scale_f32 v3, vcc, 1.0, v0, 1.0
	v_mul_f32_e32 v18, v3, v2
	v_fma_f32 v19, -v1, v18, v3
	v_fmac_f32_e32 v18, v19, v2
	v_fma_f32 v1, -v1, v18, v3
	v_div_fmas_f32 v1, v1, v2, v18
	v_div_fixup_f32 v18, v1, v0, 1.0
	v_or_b32_e32 v0, 3, v152
	v_mov_b32_e32 v1, v153
	v_lshl_add_u64 v[0:1], v[32:33], 0, v[0:1]
	v_lshlrev_b64 v[0:1], 11, v[0:1]
	v_or_b32_e32 v19, v0, v40
	v_or_b32_e32 v0, 0x600, v19
	v_lshl_add_u64 v[2:3], s[10:11], 0, v[0:1]
	s_nop 0
	v_mov_b32_e32 v3, v1
	v_lshl_add_u64 v[0:1], s[12:13], 0, v[0:1]
	v_lshlrev_b32_e32 v36, 16, v96
	v_or_b32_e32 v2, 0x640, v19
	v_lshl_add_u64 v[34:35], s[10:11], 0, v[2:3]
	s_nop 0
	v_mul_f32_e32 v34, 0xbfb8aa3b, v36
	v_exp_f32_e32 v34, v34
	v_lshlrev_b32_e32 v19, 16, v97
; __device__ __forceinline__ unsigned pk2(float lo, float hi) { return pg8::pk_bf16_rne(lo, hi); }
; __device__ __forceinline__ float bf2f(unsigned short u) { return __uint_as_float(((unsigned)u) << 16); }
; __device__ __forceinline__ float half_sum(float v) { v = row16_allsum(v); v = rows_pair_sum(v); return v; }
; __device__ __forceinline__ int crow(int r, int hi) { return (r & 3) + 8 * (r >> 2) + 4 * hi; }
; __device__ __forceinline__ void ret_out(const Params& P, int l, unsigned char* lds, int u, int tid) {
;     ...
;     for (int r = 0; r < 16; ++r) {
;         const float mean = half_sum(o0[r] + o1[r]) * (1.0f / 64.0f);
;         const float d0 = o0[r] - mean, d1 = o1[r] - mean;
;         const float var = half_sum(d0 * d0 + d1 * d1) * (1.0f / 64.0f);
;         const float rstd = 1.0f / sqrtf(var + 1e-5f);
;         const size_t t = tc + c0f + crow(r, hi);
;         const float ga = bf2f(ZR[t * 1024 + 768 + h * 64 + r32]), gb = bf2f(ZR[t * 1024 + 768 + h * 64 + 32 + r32]);
;         const float sa = ga / (1.0f + __expf(-ga)), sb = gb / (1.0f + __expf(-gb));
;         MIX[t * 1024 + 768 + h * 64 + r32] = (bf16_t)(pk2(sa * d0 * rstd * g0, 0.f) & 0xffffu);
;         MIX[t * 1024 + 768 + h * 64 + 32 + r32] = (bf16_t)(pk2(sb * d1 * rstd * g1, 0.f) & 0xffffu);
	v_add_f32_e32 v34, 1.0, v34
	v_div_scale_f32 v35, s[6:7], v34, v34, v36
	v_rcp_f32_e32 v37, v35
	s_nop 0
	v_fma_f32 v41, -v35, v37, 1.0
	v_fmac_f32_e32 v37, v41, v37
	v_div_scale_f32 v41, vcc, v36, v34, v36
	v_mul_f32_e32 v42, v41, v37
	v_fma_f32 v43, -v35, v42, v41
	v_fmac_f32_e32 v42, v43, v37
	v_fma_f32 v35, -v35, v42, v41
	v_div_fmas_f32 v35, v35, v37, v42
	v_div_fixup_f32 v34, v35, v34, v36
	v_mul_f32_e32 v35, 0xbfb8aa3b, v19
	v_exp_f32_e32 v35, v35
	v_mul_f32_e32 v17, v17, v34
	v_mul_f32_e32 v17, v18, v17
	v_mul_f32_e32 v17, v39, v17
	v_add_f32_e32 v35, 1.0, v35
	v_div_scale_f32 v36, s[6:7], v35, v35, v19
	v_rcp_f32_e32 v37, v36
	v_cvt_pk_bf16_f32 v17, v17, s0
	global_store_short v[0:1], v17, off
	v_fma_f32 v41, -v36, v37, 1.0
	v_fmac_f32_e32 v37, v41, v37
	v_div_scale_f32 v41, vcc, v19, v35, v19
	v_mul_f32_e32 v42, v41, v37
	v_fma_f32 v43, -v36, v42, v41
	v_fmac_f32_e32 v42, v43, v37
	v_fma_f32 v36, -v36, v42, v41
	v_div_fmas_f32 v36, v36, v37, v42
	v_div_fixup_f32 v19, v36, v35, v19
	v_mul_f32_e32 v0, v16, v19
	v_mul_f32_e32 v0, v18, v0
	v_mul_f32_e32 v0, v38, v0
	v_cvt_pk_bf16_f32 v16, v0, s0
	v_lshl_add_u64 v[0:1], s[12:13], 0, v[2:3]
	global_store_short v[0:1], v16, off
	v_add_f32_e32 v0, v4, v20
	s_nop 1
	v_add_f32_dpp v0, v0, v0 row_ror:8 row_mask:0xf bank_mask:0xf bound_ctrl:1
	s_nop 1
	v_add_f32_dpp v0, v0, v0 row_ror:4 row_mask:0xf bank_mask:0xf bound_ctrl:1
	s_nop 1
	v_add_f32_dpp v0, v0, v0 row_ror:2 row_mask:0xf bank_mask:0xf bound_ctrl:1
	s_nop 1
	v_add_f32_dpp v0, v0, v0 row_ror:1 row_mask:0xf bank_mask:0xf bound_ctrl:1
	v_mov_b32_e32 v1, v0
	s_nop 1
	v_permlane16_swap_b32_e32 v0, v1
	v_add_f32_e32 v0, v0, v1
	v_fmamk_f32 v16, v0, 0xbc800000, v4
	v_fmamk_f32 v4, v0, 0xbc800000, v20
	v_mul_f32_e32 v0, v4, v4
	v_fmac_f32_e32 v0, v16, v16
	s_nop 1
	v_add_f32_dpp v0, v0, v0 row_ror:8 row_mask:0xf bank_mask:0xf bound_ctrl:1
	s_nop 1
	v_add_f32_dpp v0, v0, v0 row_ror:4 row_mask:0xf bank_mask:0xf bound_ctrl:1
	s_nop 1
	v_add_f32_dpp v0, v0, v0 row_ror:2 row_mask:0xf bank_mask:0xf bound_ctrl:1
	s_nop 1
	v_add_f32_dpp v0, v0, v0 row_ror:1 row_mask:0xf bank_mask:0xf bound_ctrl:1
	v_mov_b32_e32 v1, v0
	s_nop 1
	v_permlane16_swap_b32_e32 v0, v1
	v_add_f32_e32 v0, v0, v1
	v_fmamk_f32 v0, v0, 0x3c800000, v200
	v_cmp_gt_f32_e32 vcc, s43, v0
	v_mul_f32_e32 v1, 0x4f800000, v0
	s_nop 0
	v_cndmask_b32_e32 v0, v0, v1, vcc
	v_sqrt_f32_e32 v1, v0
	s_nop 0
	v_add_u32_e32 v2, -1, v1
	v_fma_f32 v3, -v2, v1, v0
	v_cmp_ge_f32_e64 s[6:7], 0, v3
	v_add_u32_e32 v3, 1, v1
	s_nop 0
	v_cndmask_b32_e64 v2, v1, v2, s[6:7]
	v_fma_f32 v1, -v3, v1, v0
	v_cmp_lt_f32_e64 s[6:7], 0, v1
	s_nop 1
	v_cndmask_b32_e64 v1, v2, v3, s[6:7]
	v_mul_f32_e32 v2, 0x37800000, v1
	v_cndmask_b32_e32 v1, v1, v2, vcc
	v_cmp_class_f32_e32 vcc, v0, v175
	s_nop 1
	v_cndmask_b32_e32 v0, v1, v0, vcc
	v_div_scale_f32 v1, s[6:7], v0, v0, 1.0
	v_rcp_f32_e32 v2, v1
	s_nop 0
	v_fma_f32 v3, -v1, v2, 1.0
	v_fmac_f32_e32 v2, v3, v2
	v_div_scale_f32 v3, vcc, 1.0, v0, 1.0
	v_mul_f32_e32 v17, v3, v2
	v_fma_f32 v18, -v1, v17, v3
	v_fmac_f32_e32 v17, v18, v2
	v_fma_f32 v1, -v1, v17, v3
	v_div_fmas_f32 v1, v1, v2, v17
	v_div_fixup_f32 v17, v1, v0, 1.0
	v_or_b32_e32 v0, 8, v152
	v_mov_b32_e32 v1, v153
	v_lshl_add_u64 v[0:1], v[32:33], 0, v[0:1]
	v_lshlrev_b64 v[0:1], 11, v[0:1]
	v_or_b32_e32 v18, v0, v40
	v_or_b32_e32 v0, 0x600, v18
	v_lshl_add_u64 v[2:3], s[10:11], 0, v[0:1]
	s_nop 0
	v_mov_b32_e32 v3, v1
	v_lshl_add_u64 v[0:1], s[12:13], 0, v[0:1]
	v_lshlrev_b32_e32 v20, 16, v98
	v_or_b32_e32 v2, 0x640, v18
	v_lshl_add_u64 v[18:19], s[10:11], 0, v[2:3]
	s_nop 0
	v_mul_f32_e32 v19, 0xbfb8aa3b, v20
	v_exp_f32_e32 v19, v19
	v_lshlrev_b32_e32 v18, 16, v99
	v_add_f32_e32 v19, 1.0, v19
	v_div_scale_f32 v34, s[6:7], v19, v19, v20
	v_rcp_f32_e32 v35, v34
	s_nop 0
	v_fma_f32 v36, -v34, v35, 1.0
	v_fmac_f32_e32 v35, v36, v35
	v_div_scale_f32 v36, vcc, v20, v19, v20
	v_mul_f32_e32 v37, v36, v35
	v_fma_f32 v41, -v34, v37, v36
	v_fmac_f32_e32 v37, v41, v35
	v_fma_f32 v34, -v34, v37, v36
	v_div_fmas_f32 v34, v34, v35, v37
	v_div_fixup_f32 v19, v34, v19, v20
	v_mul_f32_e32 v20, 0xbfb8aa3b, v18
	v_exp_f32_e32 v20, v20
	v_mul_f32_e32 v16, v16, v19
	v_mul_f32_e32 v16, v17, v16
	v_mul_f32_e32 v16, v39, v16
	v_add_f32_e32 v20, 1.0, v20
	v_div_scale_f32 v34, s[6:7], v20, v20, v18
	v_rcp_f32_e32 v35, v34
	v_cvt_pk_bf16_f32 v16, v16, s0
	global_store_short v[0:1], v16, off
	v_fma_f32 v36, -v34, v35, 1.0
	v_fmac_f32_e32 v35, v36, v35
	v_div_scale_f32 v36, vcc, v18, v20, v18
	v_mul_f32_e32 v37, v36, v35
	v_fma_f32 v41, -v34, v37, v36
	v_fmac_f32_e32 v37, v41, v35
	v_fma_f32 v34, -v34, v37, v36
	v_div_fmas_f32 v34, v34, v35, v37
	v_div_fixup_f32 v18, v34, v20, v18
	v_mul_f32_e32 v0, v4, v18
	v_mul_f32_e32 v0, v17, v0
	v_mul_f32_e32 v0, v38, v0
	v_cvt_pk_bf16_f32 v4, v0, s0
	v_lshl_add_u64 v[0:1], s[12:13], 0, v[2:3]
	global_store_short v[0:1], v4, off
	v_add_f32_e32 v0, v5, v21
	s_nop 1
	v_add_f32_dpp v0, v0, v0 row_ror:8 row_mask:0xf bank_mask:0xf bound_ctrl:1
	s_nop 1
	v_add_f32_dpp v0, v0, v0 row_ror:4 row_mask:0xf bank_mask:0xf bound_ctrl:1
	s_nop 1
	v_add_f32_dpp v0, v0, v0 row_ror:2 row_mask:0xf bank_mask:0xf bound_ctrl:1
	s_nop 1
	v_add_f32_dpp v0, v0, v0 row_ror:1 row_mask:0xf bank_mask:0xf bound_ctrl:1
	v_mov_b32_e32 v1, v0
	s_nop 1
	v_permlane16_swap_b32_e32 v0, v1
	v_add_f32_e32 v0, v0, v1
	v_fmamk_f32 v4, v0, 0xbc800000, v21
	v_fmamk_f32 v5, v0, 0xbc800000, v5
	v_mul_f32_e32 v0, v4, v4
	v_fmac_f32_e32 v0, v5, v5
	s_nop 1
	v_add_f32_dpp v0, v0, v0 row_ror:8 row_mask:0xf bank_mask:0xf bound_ctrl:1
	s_nop 1
	v_add_f32_dpp v0, v0, v0 row_ror:4 row_mask:0xf bank_mask:0xf bound_ctrl:1
	s_nop 1
; __device__ __forceinline__ unsigned pk2(float lo, float hi) { return pg8::pk_bf16_rne(lo, hi); }
; __device__ __forceinline__ float bf2f(unsigned short u) { return __uint_as_float(((unsigned)u) << 16); }
; __device__ __forceinline__ float half_sum(float v) { v = row16_allsum(v); v = rows_pair_sum(v); return v; }
; __device__ __forceinline__ int crow(int r, int hi) { return (r & 3) + 8 * (r >> 2) + 4 * hi; }
; __device__ __forceinline__ void ret_out(const Params& P, int l, unsigned char* lds, int u, int tid) {
;     ...
;     for (int r = 0; r < 16; ++r) {
;         const float mean = half_sum(o0[r] + o1[r]) * (1.0f / 64.0f);
;         const float d0 = o0[r] - mean, d1 = o1[r] - mean;
;         const float var = half_sum(d0 * d0 + d1 * d1) * (1.0f / 64.0f);
;         const float rstd = 1.0f / sqrtf(var + 1e-5f);
;         const size_t t = tc + c0f + crow(r, hi);
;         const float ga = bf2f(ZR[t * 1024 + 768 + h * 64 + r32]), gb = bf2f(ZR[t * 1024 + 768 + h * 64 + 32 + r32]);
;         const float sa = ga / (1.0f + __expf(-ga)), sb = gb / (1.0f + __expf(-gb));
;         MIX[t * 1024 + 768 + h * 64 + r32] = (bf16_t)(pk2(sa * d0 * rstd * g0, 0.f) & 0xffffu);
;         MIX[t * 1024 + 768 + h * 64 + 32 + r32] = (bf16_t)(pk2(sb * d1 * rstd * g1, 0.f) & 0xffffu);
	v_add_f32_dpp v0, v0, v0 row_ror:2 row_mask:0xf bank_mask:0xf bound_ctrl:1
	s_nop 1
	v_add_f32_dpp v0, v0, v0 row_ror:1 row_mask:0xf bank_mask:0xf bound_ctrl:1
	v_mov_b32_e32 v1, v0
	s_nop 1
	v_permlane16_swap_b32_e32 v0, v1
	v_add_f32_e32 v0, v0, v1
	v_fmamk_f32 v0, v0, 0x3c800000, v200
	v_cmp_gt_f32_e32 vcc, s43, v0
	v_mul_f32_e32 v1, 0x4f800000, v0
	s_nop 0
	v_cndmask_b32_e32 v0, v0, v1, vcc
	v_sqrt_f32_e32 v1, v0
	s_nop 0
	v_add_u32_e32 v2, -1, v1
	v_fma_f32 v3, -v2, v1, v0
	v_cmp_ge_f32_e64 s[6:7], 0, v3
	v_add_u32_e32 v3, 1, v1
	s_nop 0
	v_cndmask_b32_e64 v2, v1, v2, s[6:7]
	v_fma_f32 v1, -v3, v1, v0
	v_cmp_lt_f32_e64 s[6:7], 0, v1
	s_nop 1
	v_cndmask_b32_e64 v1, v2, v3, s[6:7]
	v_mul_f32_e32 v2, 0x37800000, v1
	v_cndmask_b32_e32 v1, v1, v2, vcc
	v_cmp_class_f32_e32 vcc, v0, v175
	s_nop 1
	v_cndmask_b32_e32 v0, v1, v0, vcc
	v_div_scale_f32 v1, s[6:7], v0, v0, 1.0
	v_rcp_f32_e32 v2, v1
	s_nop 0
	v_fma_f32 v3, -v1, v2, 1.0
	v_fmac_f32_e32 v2, v3, v2
	v_div_scale_f32 v3, vcc, 1.0, v0, 1.0
	v_mul_f32_e32 v16, v3, v2
	v_fma_f32 v17, -v1, v16, v3
	v_fmac_f32_e32 v16, v17, v2
	v_fma_f32 v1, -v1, v16, v3
	v_div_fmas_f32 v1, v1, v2, v16
	v_div_fixup_f32 v16, v1, v0, 1.0
	v_or_b32_e32 v0, 9, v152
	v_mov_b32_e32 v1, v153
	v_lshl_add_u64 v[0:1], v[32:33], 0, v[0:1]
	v_lshlrev_b64 v[0:1], 11, v[0:1]
	v_or_b32_e32 v17, v0, v40
	v_or_b32_e32 v0, 0x600, v17
	v_lshl_add_u64 v[2:3], s[10:11], 0, v[0:1]
	s_nop 0
	v_mov_b32_e32 v3, v1
	v_lshl_add_u64 v[0:1], s[12:13], 0, v[0:1]
	v_lshlrev_b32_e32 v20, 16, v100
	v_or_b32_e32 v2, 0x640, v17
	v_lshl_add_u64 v[18:19], s[10:11], 0, v[2:3]
	s_nop 0
	v_mul_f32_e32 v18, 0xbfb8aa3b, v20
	v_exp_f32_e32 v18, v18
	v_lshlrev_b32_e32 v17, 16, v101
	v_add_f32_e32 v18, 1.0, v18
	v_div_scale_f32 v19, s[6:7], v18, v18, v20
	v_rcp_f32_e32 v21, v19
	s_nop 0
	v_fma_f32 v34, -v19, v21, 1.0
	v_fmac_f32_e32 v21, v34, v21
	v_div_scale_f32 v34, vcc, v20, v18, v20
	v_mul_f32_e32 v35, v34, v21
	v_fma_f32 v36, -v19, v35, v34
	v_fmac_f32_e32 v35, v36, v21
	v_fma_f32 v19, -v19, v35, v34
	v_div_fmas_f32 v19, v19, v21, v35
	v_div_fixup_f32 v18, v19, v18, v20
	v_mul_f32_e32 v19, 0xbfb8aa3b, v17
	v_exp_f32_e32 v19, v19
	v_mul_f32_e32 v5, v5, v18
	v_mul_f32_e32 v5, v16, v5
	v_mul_f32_e32 v5, v39, v5
	v_add_f32_e32 v19, 1.0, v19
	v_div_scale_f32 v20, s[6:7], v19, v19, v17
	v_rcp_f32_e32 v21, v20
	v_cvt_pk_bf16_f32 v5, v5, s0
	global_store_short v[0:1], v5, off
	v_fma_f32 v34, -v20, v21, 1.0
	v_fmac_f32_e32 v21, v34, v21
	v_div_scale_f32 v34, vcc, v17, v19, v17
	v_mul_f32_e32 v35, v34, v21
	v_fma_f32 v36, -v20, v35, v34
	v_fmac_f32_e32 v35, v36, v21
	v_fma_f32 v20, -v20, v35, v34
	v_div_fmas_f32 v20, v20, v21, v35
	v_div_fixup_f32 v17, v20, v19, v17
	v_mul_f32_e32 v0, v4, v17
	v_mul_f32_e32 v0, v16, v0
	v_mul_f32_e32 v0, v38, v0
	v_cvt_pk_bf16_f32 v4, v0, s0
	v_lshl_add_u64 v[0:1], s[12:13], 0, v[2:3]
	global_store_short v[0:1], v4, off
	v_add_f32_e32 v0, v6, v22
	s_nop 1
	v_add_f32_dpp v0, v0, v0 row_ror:8 row_mask:0xf bank_mask:0xf bound_ctrl:1
	s_nop 1
	v_add_f32_dpp v0, v0, v0 row_ror:4 row_mask:0xf bank_mask:0xf bound_ctrl:1
	s_nop 1
	v_add_f32_dpp v0, v0, v0 row_ror:2 row_mask:0xf bank_mask:0xf bound_ctrl:1
	s_nop 1
	v_add_f32_dpp v0, v0, v0 row_ror:1 row_mask:0xf bank_mask:0xf bound_ctrl:1
	v_mov_b32_e32 v1, v0
	s_nop 1
	v_permlane16_swap_b32_e32 v0, v1
	v_add_f32_e32 v0, v0, v1
	v_fmamk_f32 v4, v0, 0xbc800000, v22
	v_fmamk_f32 v5, v0, 0xbc800000, v6
	v_mul_f32_e32 v0, v4, v4
	v_fmac_f32_e32 v0, v5, v5
	s_nop 1
	v_add_f32_dpp v0, v0, v0 row_ror:8 row_mask:0xf bank_mask:0xf bound_ctrl:1
	s_nop 1
	v_add_f32_dpp v0, v0, v0 row_ror:4 row_mask:0xf bank_mask:0xf bound_ctrl:1
	s_nop 1
	v_add_f32_dpp v0, v0, v0 row_ror:2 row_mask:0xf bank_mask:0xf bound_ctrl:1
	s_nop 1
	v_add_f32_dpp v0, v0, v0 row_ror:1 row_mask:0xf bank_mask:0xf bound_ctrl:1
	v_mov_b32_e32 v1, v0
	s_nop 1
	v_permlane16_swap_b32_e32 v0, v1
	v_add_f32_e32 v0, v0, v1
	v_fmamk_f32 v0, v0, 0x3c800000, v200
	v_cmp_gt_f32_e32 vcc, s43, v0
	v_mul_f32_e32 v1, 0x4f800000, v0
	s_nop 0
	v_cndmask_b32_e32 v0, v0, v1, vcc
	v_sqrt_f32_e32 v1, v0
	s_nop 0
	v_add_u32_e32 v2, -1, v1
	v_fma_f32 v3, -v2, v1, v0
	v_cmp_ge_f32_e64 s[6:7], 0, v3
	v_add_u32_e32 v3, 1, v1
	s_nop 0
	v_cndmask_b32_e64 v2, v1, v2, s[6:7]
	v_fma_f32 v1, -v3, v1, v0
	v_cmp_lt_f32_e64 s[6:7], 0, v1
	s_nop 1
	v_cndmask_b32_e64 v1, v2, v3, s[6:7]
	v_mul_f32_e32 v2, 0x37800000, v1
	v_cndmask_b32_e32 v1, v1, v2, vcc
	v_cmp_class_f32_e32 vcc, v0, v175
	s_nop 1
	v_cndmask_b32_e32 v0, v1, v0, vcc
	v_div_scale_f32 v1, s[6:7], v0, v0, 1.0
	v_rcp_f32_e32 v2, v1
	s_nop 0
	v_fma_f32 v3, -v1, v2, 1.0
	v_fmac_f32_e32 v2, v3, v2
	v_div_scale_f32 v3, vcc, 1.0, v0, 1.0
	v_mul_f32_e32 v6, v3, v2
	v_fma_f32 v16, -v1, v6, v3
	v_fmac_f32_e32 v6, v16, v2
	v_fma_f32 v1, -v1, v6, v3
	v_div_fmas_f32 v1, v1, v2, v6
	v_div_fixup_f32 v6, v1, v0, 1.0
	v_or_b32_e32 v0, 10, v152
	v_mov_b32_e32 v1, v153
	v_lshl_add_u64 v[0:1], v[32:33], 0, v[0:1]
	v_lshlrev_b64 v[0:1], 11, v[0:1]
	v_or_b32_e32 v16, v0, v40
	v_or_b32_e32 v0, 0x600, v16
	v_lshl_add_u64 v[2:3], s[10:11], 0, v[0:1]
	s_nop 0
	v_mov_b32_e32 v3, v1
	v_lshl_add_u64 v[0:1], s[12:13], 0, v[0:1]
	v_lshlrev_b32_e32 v18, 16, v102
	v_or_b32_e32 v2, 0x640, v16
	v_lshl_add_u64 v[16:17], s[10:11], 0, v[2:3]
	s_nop 0
	v_mul_f32_e32 v17, 0xbfb8aa3b, v18
	v_exp_f32_e32 v17, v17
	v_lshlrev_b32_e32 v16, 16, v103
	v_add_f32_e32 v17, 1.0, v17
	v_div_scale_f32 v19, s[6:7], v17, v17, v18
	v_rcp_f32_e32 v20, v19
	s_nop 0
	v_fma_f32 v21, -v19, v20, 1.0
	v_fmac_f32_e32 v20, v21, v20
	v_div_scale_f32 v21, vcc, v18, v17, v18
	v_mul_f32_e32 v22, v21, v20
	v_fma_f32 v34, -v19, v22, v21
	v_fmac_f32_e32 v22, v34, v20
; __device__ __forceinline__ unsigned pk2(float lo, float hi) { return pg8::pk_bf16_rne(lo, hi); }
; __device__ __forceinline__ float bf2f(unsigned short u) { return __uint_as_float(((unsigned)u) << 16); }
; __device__ __forceinline__ float half_sum(float v) { v = row16_allsum(v); v = rows_pair_sum(v); return v; }
; __device__ __forceinline__ int crow(int r, int hi) { return (r & 3) + 8 * (r >> 2) + 4 * hi; }
; __device__ __forceinline__ void ret_out(const Params& P, int l, unsigned char* lds, int u, int tid) {
;     ...
;     for (int r = 0; r < 16; ++r) {
;         const float mean = half_sum(o0[r] + o1[r]) * (1.0f / 64.0f);
;         const float d0 = o0[r] - mean, d1 = o1[r] - mean;
;         const float var = half_sum(d0 * d0 + d1 * d1) * (1.0f / 64.0f);
;         const float rstd = 1.0f / sqrtf(var + 1e-5f);
;         const size_t t = tc + c0f + crow(r, hi);
;         const float ga = bf2f(ZR[t * 1024 + 768 + h * 64 + r32]), gb = bf2f(ZR[t * 1024 + 768 + h * 64 + 32 + r32]);
;         const float sa = ga / (1.0f + __expf(-ga)), sb = gb / (1.0f + __expf(-gb));
;         MIX[t * 1024 + 768 + h * 64 + r32] = (bf16_t)(pk2(sa * d0 * rstd * g0, 0.f) & 0xffffu);
;         MIX[t * 1024 + 768 + h * 64 + 32 + r32] = (bf16_t)(pk2(sb * d1 * rstd * g1, 0.f) & 0xffffu);
	v_fma_f32 v19, -v19, v22, v21
	v_div_fmas_f32 v19, v19, v20, v22
	v_div_fixup_f32 v17, v19, v17, v18
	v_mul_f32_e32 v18, 0xbfb8aa3b, v16
	v_exp_f32_e32 v18, v18
	v_mul_f32_e32 v5, v5, v17
	v_mul_f32_e32 v5, v6, v5
	v_mul_f32_e32 v5, v39, v5
	v_add_f32_e32 v18, 1.0, v18
	v_div_scale_f32 v19, s[6:7], v18, v18, v16
	v_rcp_f32_e32 v20, v19
	v_cvt_pk_bf16_f32 v5, v5, s0
	global_store_short v[0:1], v5, off
	v_fma_f32 v21, -v19, v20, 1.0
	v_fmac_f32_e32 v20, v21, v20
	v_div_scale_f32 v21, vcc, v16, v18, v16
	v_mul_f32_e32 v22, v21, v20
	v_fma_f32 v34, -v19, v22, v21
	v_fmac_f32_e32 v22, v34, v20
	v_fma_f32 v19, -v19, v22, v21
	v_div_fmas_f32 v19, v19, v20, v22
	v_div_fixup_f32 v16, v19, v18, v16
	v_mul_f32_e32 v0, v4, v16
	v_mul_f32_e32 v0, v6, v0
	v_mul_f32_e32 v0, v38, v0
	v_cvt_pk_bf16_f32 v4, v0, s0
	v_lshl_add_u64 v[0:1], s[12:13], 0, v[2:3]
	global_store_short v[0:1], v4, off
	v_add_f32_e32 v0, v7, v23
	s_nop 1
	v_add_f32_dpp v0, v0, v0 row_ror:8 row_mask:0xf bank_mask:0xf bound_ctrl:1
	s_nop 1
	v_add_f32_dpp v0, v0, v0 row_ror:4 row_mask:0xf bank_mask:0xf bound_ctrl:1
	s_nop 1
	v_add_f32_dpp v0, v0, v0 row_ror:2 row_mask:0xf bank_mask:0xf bound_ctrl:1
	s_nop 1
	v_add_f32_dpp v0, v0, v0 row_ror:1 row_mask:0xf bank_mask:0xf bound_ctrl:1
	v_mov_b32_e32 v1, v0
	s_nop 1
	v_permlane16_swap_b32_e32 v0, v1
	v_add_f32_e32 v0, v0, v1
	v_fmamk_f32 v4, v0, 0xbc800000, v23
	v_fmamk_f32 v5, v0, 0xbc800000, v7
	v_mul_f32_e32 v0, v4, v4
	v_fmac_f32_e32 v0, v5, v5
	s_nop 1
	v_add_f32_dpp v0, v0, v0 row_ror:8 row_mask:0xf bank_mask:0xf bound_ctrl:1
	s_nop 1
	v_add_f32_dpp v0, v0, v0 row_ror:4 row_mask:0xf bank_mask:0xf bound_ctrl:1
	s_nop 1
	v_add_f32_dpp v0, v0, v0 row_ror:2 row_mask:0xf bank_mask:0xf bound_ctrl:1
	s_nop 1
	v_add_f32_dpp v0, v0, v0 row_ror:1 row_mask:0xf bank_mask:0xf bound_ctrl:1
	v_mov_b32_e32 v1, v0
	s_nop 1
	v_permlane16_swap_b32_e32 v0, v1
	v_add_f32_e32 v0, v0, v1
	v_fmamk_f32 v0, v0, 0x3c800000, v200
	v_cmp_gt_f32_e32 vcc, s43, v0
	v_mul_f32_e32 v1, 0x4f800000, v0
	s_nop 0
	v_cndmask_b32_e32 v0, v0, v1, vcc
	v_sqrt_f32_e32 v1, v0
	s_nop 0
	v_add_u32_e32 v2, -1, v1
	v_fma_f32 v3, -v2, v1, v0
	v_cmp_ge_f32_e64 s[6:7], 0, v3
	v_add_u32_e32 v3, 1, v1
	s_nop 0
	v_cndmask_b32_e64 v2, v1, v2, s[6:7]
	v_fma_f32 v1, -v3, v1, v0
	v_cmp_lt_f32_e64 s[6:7], 0, v1
	s_nop 1
	v_cndmask_b32_e64 v1, v2, v3, s[6:7]
	v_mul_f32_e32 v2, 0x37800000, v1
	v_cndmask_b32_e32 v1, v1, v2, vcc
	v_cmp_class_f32_e32 vcc, v0, v175
	s_nop 1
	v_cndmask_b32_e32 v0, v1, v0, vcc
	v_div_scale_f32 v1, s[6:7], v0, v0, 1.0
	v_rcp_f32_e32 v2, v1
	s_nop 0
	v_fma_f32 v3, -v1, v2, 1.0
	v_fmac_f32_e32 v2, v3, v2
	v_div_scale_f32 v3, vcc, 1.0, v0, 1.0
	v_mul_f32_e32 v6, v3, v2
	v_fma_f32 v7, -v1, v6, v3
	v_fmac_f32_e32 v6, v7, v2
	v_fma_f32 v1, -v1, v6, v3
	v_div_fmas_f32 v1, v1, v2, v6
	v_div_fixup_f32 v6, v1, v0, 1.0
	v_or_b32_e32 v0, 11, v152
	v_mov_b32_e32 v1, v153
	v_lshl_add_u64 v[0:1], v[32:33], 0, v[0:1]
	v_lshlrev_b64 v[0:1], 11, v[0:1]
	v_or_b32_e32 v7, v0, v40
	v_or_b32_e32 v0, 0x600, v7
	v_lshl_add_u64 v[2:3], s[10:11], 0, v[0:1]
	s_nop 0
	v_mov_b32_e32 v3, v1
	v_lshl_add_u64 v[0:1], s[12:13], 0, v[0:1]
	v_lshlrev_b32_e32 v18, 16, v104
	v_or_b32_e32 v2, 0x640, v7
	v_lshl_add_u64 v[16:17], s[10:11], 0, v[2:3]
	s_nop 0
	v_mul_f32_e32 v16, 0xbfb8aa3b, v18
	v_exp_f32_e32 v16, v16
	v_lshlrev_b32_e32 v7, 16, v105
	v_add_f32_e32 v16, 1.0, v16
	v_div_scale_f32 v17, s[6:7], v16, v16, v18
	v_rcp_f32_e32 v19, v17
	s_nop 0
	v_fma_f32 v20, -v17, v19, 1.0
	v_fmac_f32_e32 v19, v20, v19
	v_div_scale_f32 v20, vcc, v18, v16, v18
	v_mul_f32_e32 v21, v20, v19
	v_fma_f32 v22, -v17, v21, v20
	v_fmac_f32_e32 v21, v22, v19
	v_fma_f32 v17, -v17, v21, v20
	v_div_fmas_f32 v17, v17, v19, v21
	v_div_fixup_f32 v16, v17, v16, v18
	v_mul_f32_e32 v17, 0xbfb8aa3b, v7
	v_exp_f32_e32 v17, v17
	v_mul_f32_e32 v5, v5, v16
	v_mul_f32_e32 v5, v6, v5
	v_mul_f32_e32 v5, v39, v5
	v_add_f32_e32 v17, 1.0, v17
	v_div_scale_f32 v18, s[6:7], v17, v17, v7
	v_rcp_f32_e32 v19, v18
	v_cvt_pk_bf16_f32 v5, v5, s0
	global_store_short v[0:1], v5, off
	v_fma_f32 v20, -v18, v19, 1.0
	v_fmac_f32_e32 v19, v20, v19
	v_div_scale_f32 v20, vcc, v7, v17, v7
	v_mul_f32_e32 v21, v20, v19
	v_fma_f32 v22, -v18, v21, v20
	v_fmac_f32_e32 v21, v22, v19
	v_fma_f32 v18, -v18, v21, v20
	v_div_fmas_f32 v18, v18, v19, v21
	v_div_fixup_f32 v7, v18, v17, v7
	v_mul_f32_e32 v0, v4, v7
	v_mul_f32_e32 v0, v6, v0
	v_mul_f32_e32 v0, v38, v0
	v_cvt_pk_bf16_f32 v4, v0, s0
	v_lshl_add_u64 v[0:1], s[12:13], 0, v[2:3]
	global_store_short v[0:1], v4, off
	v_add_f32_e32 v0, v8, v24
	s_nop 1
	v_add_f32_dpp v0, v0, v0 row_ror:8 row_mask:0xf bank_mask:0xf bound_ctrl:1
	s_nop 1
	v_add_f32_dpp v0, v0, v0 row_ror:4 row_mask:0xf bank_mask:0xf bound_ctrl:1
	s_nop 1
	v_add_f32_dpp v0, v0, v0 row_ror:2 row_mask:0xf bank_mask:0xf bound_ctrl:1
	s_nop 1
	v_add_f32_dpp v0, v0, v0 row_ror:1 row_mask:0xf bank_mask:0xf bound_ctrl:1
	v_mov_b32_e32 v1, v0
	s_nop 1
	v_permlane16_swap_b32_e32 v0, v1
	v_add_f32_e32 v0, v0, v1
	v_fmamk_f32 v4, v0, 0xbc800000, v24
	v_fmamk_f32 v5, v0, 0xbc800000, v8
	v_mul_f32_e32 v0, v4, v4
	v_fmac_f32_e32 v0, v5, v5
	s_nop 1
	v_add_f32_dpp v0, v0, v0 row_ror:8 row_mask:0xf bank_mask:0xf bound_ctrl:1
	s_nop 1
	v_add_f32_dpp v0, v0, v0 row_ror:4 row_mask:0xf bank_mask:0xf bound_ctrl:1
	s_nop 1
	v_add_f32_dpp v0, v0, v0 row_ror:2 row_mask:0xf bank_mask:0xf bound_ctrl:1
	s_nop 1
	v_add_f32_dpp v0, v0, v0 row_ror:1 row_mask:0xf bank_mask:0xf bound_ctrl:1
	v_mov_b32_e32 v1, v0
	s_nop 1
	v_permlane16_swap_b32_e32 v0, v1
	v_add_f32_e32 v0, v0, v1
	v_fmamk_f32 v0, v0, 0x3c800000, v200
	v_cmp_gt_f32_e32 vcc, s43, v0
	v_mul_f32_e32 v1, 0x4f800000, v0
; __device__ __forceinline__ unsigned pk2(float lo, float hi) { return pg8::pk_bf16_rne(lo, hi); }
; __device__ __forceinline__ float bf2f(unsigned short u) { return __uint_as_float(((unsigned)u) << 16); }
; __device__ __forceinline__ float half_sum(float v) { v = row16_allsum(v); v = rows_pair_sum(v); return v; }
; __device__ __forceinline__ int crow(int r, int hi) { return (r & 3) + 8 * (r >> 2) + 4 * hi; }
; __device__ __forceinline__ void ret_out(const Params& P, int l, unsigned char* lds, int u, int tid) {
;     ...
;     for (int r = 0; r < 16; ++r) {
;         const float mean = half_sum(o0[r] + o1[r]) * (1.0f / 64.0f);
;         const float d0 = o0[r] - mean, d1 = o1[r] - mean;
;         const float var = half_sum(d0 * d0 + d1 * d1) * (1.0f / 64.0f);
;         const float rstd = 1.0f / sqrtf(var + 1e-5f);
;         const size_t t = tc + c0f + crow(r, hi);
;         const float ga = bf2f(ZR[t * 1024 + 768 + h * 64 + r32]), gb = bf2f(ZR[t * 1024 + 768 + h * 64 + 32 + r32]);
;         const float sa = ga / (1.0f + __expf(-ga)), sb = gb / (1.0f + __expf(-gb));
;         MIX[t * 1024 + 768 + h * 64 + r32] = (bf16_t)(pk2(sa * d0 * rstd * g0, 0.f) & 0xffffu);
;         MIX[t * 1024 + 768 + h * 64 + 32 + r32] = (bf16_t)(pk2(sb * d1 * rstd * g1, 0.f) & 0xffffu);
	s_nop 0
	v_cndmask_b32_e32 v0, v0, v1, vcc
	v_sqrt_f32_e32 v1, v0
	s_nop 0
	v_add_u32_e32 v2, -1, v1
	v_fma_f32 v3, -v2, v1, v0
	v_cmp_ge_f32_e64 s[6:7], 0, v3
	v_add_u32_e32 v3, 1, v1
	s_nop 0
	v_cndmask_b32_e64 v2, v1, v2, s[6:7]
	v_fma_f32 v1, -v3, v1, v0
	v_cmp_lt_f32_e64 s[6:7], 0, v1
	s_nop 1
	v_cndmask_b32_e64 v1, v2, v3, s[6:7]
	v_mul_f32_e32 v2, 0x37800000, v1
	v_cndmask_b32_e32 v1, v1, v2, vcc
	v_cmp_class_f32_e32 vcc, v0, v175
	s_nop 1
	v_cndmask_b32_e32 v0, v1, v0, vcc
	v_div_scale_f32 v1, s[6:7], v0, v0, 1.0
	v_rcp_f32_e32 v2, v1
	s_nop 0
	v_fma_f32 v3, -v1, v2, 1.0
	v_fmac_f32_e32 v2, v3, v2
	v_div_scale_f32 v3, vcc, 1.0, v0, 1.0
	v_mul_f32_e32 v6, v3, v2
	v_fma_f32 v7, -v1, v6, v3
	v_fmac_f32_e32 v6, v7, v2
	v_fma_f32 v1, -v1, v6, v3
	v_div_fmas_f32 v1, v1, v2, v6
	v_div_fixup_f32 v6, v1, v0, 1.0
	v_or_b32_e32 v0, 16, v152
	v_mov_b32_e32 v1, v153
	v_lshl_add_u64 v[0:1], v[32:33], 0, v[0:1]
	v_lshlrev_b64 v[0:1], 11, v[0:1]
	v_or_b32_e32 v7, v0, v40
	v_or_b32_e32 v0, 0x600, v7
	v_lshl_add_u64 v[2:3], s[10:11], 0, v[0:1]
	s_nop 0
	v_mov_b32_e32 v3, v1
	v_lshl_add_u64 v[0:1], s[12:13], 0, v[0:1]
	v_lshlrev_b32_e32 v8, 16, v106
	v_or_b32_e32 v2, 0x640, v7
	v_lshl_add_u64 v[16:17], s[10:11], 0, v[2:3]
	s_nop 0
	v_mul_f32_e32 v16, 0xbfb8aa3b, v8
	v_exp_f32_e32 v16, v16
	v_lshlrev_b32_e32 v7, 16, v107
	v_add_f32_e32 v16, 1.0, v16
	v_div_scale_f32 v17, s[6:7], v16, v16, v8
	v_rcp_f32_e32 v18, v17
	s_nop 0
	v_fma_f32 v19, -v17, v18, 1.0
	v_fmac_f32_e32 v18, v19, v18
	v_div_scale_f32 v19, vcc, v8, v16, v8
	v_mul_f32_e32 v20, v19, v18
	v_fma_f32 v21, -v17, v20, v19
	v_fmac_f32_e32 v20, v21, v18
	v_fma_f32 v17, -v17, v20, v19
	v_div_fmas_f32 v17, v17, v18, v20
	v_div_fixup_f32 v8, v17, v16, v8
	v_mul_f32_e32 v16, 0xbfb8aa3b, v7
	v_exp_f32_e32 v16, v16
	v_mul_f32_e32 v5, v5, v8
	v_mul_f32_e32 v5, v6, v5
	v_mul_f32_e32 v5, v39, v5
	v_add_f32_e32 v16, 1.0, v16
	v_div_scale_f32 v17, s[6:7], v16, v16, v7
	v_rcp_f32_e32 v18, v17
	v_cvt_pk_bf16_f32 v5, v5, s0
	global_store_short v[0:1], v5, off
	v_fma_f32 v19, -v17, v18, 1.0
	v_fmac_f32_e32 v18, v19, v18
	v_div_scale_f32 v19, vcc, v7, v16, v7
	v_mul_f32_e32 v20, v19, v18
	v_fma_f32 v21, -v17, v20, v19
	v_fmac_f32_e32 v20, v21, v18
	v_fma_f32 v17, -v17, v20, v19
	v_div_fmas_f32 v17, v17, v18, v20
	v_div_fixup_f32 v7, v17, v16, v7
	v_mul_f32_e32 v0, v4, v7
	v_mul_f32_e32 v0, v6, v0
	v_mul_f32_e32 v0, v38, v0
	v_cvt_pk_bf16_f32 v4, v0, s0
	v_lshl_add_u64 v[0:1], s[12:13], 0, v[2:3]
	global_store_short v[0:1], v4, off
	v_add_f32_e32 v0, v9, v25
	s_nop 1
	v_add_f32_dpp v0, v0, v0 row_ror:8 row_mask:0xf bank_mask:0xf bound_ctrl:1
	s_nop 1
	v_add_f32_dpp v0, v0, v0 row_ror:4 row_mask:0xf bank_mask:0xf bound_ctrl:1
	s_nop 1
	v_add_f32_dpp v0, v0, v0 row_ror:2 row_mask:0xf bank_mask:0xf bound_ctrl:1
	s_nop 1
	v_add_f32_dpp v0, v0, v0 row_ror:1 row_mask:0xf bank_mask:0xf bound_ctrl:1
	v_mov_b32_e32 v1, v0
	s_nop 1
	v_permlane16_swap_b32_e32 v0, v1
	v_add_f32_e32 v0, v0, v1
	v_fmamk_f32 v4, v0, 0xbc800000, v25
	v_fmamk_f32 v5, v0, 0xbc800000, v9
	v_mul_f32_e32 v0, v4, v4
	v_fmac_f32_e32 v0, v5, v5
	s_nop 1
	v_add_f32_dpp v0, v0, v0 row_ror:8 row_mask:0xf bank_mask:0xf bound_ctrl:1
	s_nop 1
	v_add_f32_dpp v0, v0, v0 row_ror:4 row_mask:0xf bank_mask:0xf bound_ctrl:1
	s_nop 1
	v_add_f32_dpp v0, v0, v0 row_ror:2 row_mask:0xf bank_mask:0xf bound_ctrl:1
	s_nop 1
	v_add_f32_dpp v0, v0, v0 row_ror:1 row_mask:0xf bank_mask:0xf bound_ctrl:1
	v_mov_b32_e32 v1, v0
	s_nop 1
	v_permlane16_swap_b32_e32 v0, v1
	v_add_f32_e32 v0, v0, v1
	v_fmamk_f32 v0, v0, 0x3c800000, v200
	v_cmp_gt_f32_e32 vcc, s43, v0
	v_mul_f32_e32 v1, 0x4f800000, v0
	s_nop 0
	v_cndmask_b32_e32 v0, v0, v1, vcc
	v_sqrt_f32_e32 v1, v0
	s_nop 0
	v_add_u32_e32 v2, -1, v1
	v_fma_f32 v3, -v2, v1, v0
	v_cmp_ge_f32_e64 s[6:7], 0, v3
	v_add_u32_e32 v3, 1, v1
	s_nop 0
	v_cndmask_b32_e64 v2, v1, v2, s[6:7]
	v_fma_f32 v1, -v3, v1, v0
	v_cmp_lt_f32_e64 s[6:7], 0, v1
	s_nop 1
	v_cndmask_b32_e64 v1, v2, v3, s[6:7]
	v_mul_f32_e32 v2, 0x37800000, v1
	v_cndmask_b32_e32 v1, v1, v2, vcc
	v_cmp_class_f32_e32 vcc, v0, v175
	s_nop 1
	v_cndmask_b32_e32 v0, v1, v0, vcc
	v_div_scale_f32 v1, s[6:7], v0, v0, 1.0
	v_rcp_f32_e32 v2, v1
	s_nop 0
	v_fma_f32 v3, -v1, v2, 1.0
	v_fmac_f32_e32 v2, v3, v2
	v_div_scale_f32 v3, vcc, 1.0, v0, 1.0
	v_mul_f32_e32 v6, v3, v2
	v_fma_f32 v7, -v1, v6, v3
	v_fmac_f32_e32 v6, v7, v2
	v_fma_f32 v1, -v1, v6, v3
	v_div_fmas_f32 v1, v1, v2, v6
	v_div_fixup_f32 v6, v1, v0, 1.0
	v_or_b32_e32 v0, 17, v152
	v_mov_b32_e32 v1, v153
	v_lshl_add_u64 v[0:1], v[32:33], 0, v[0:1]
	v_lshlrev_b64 v[0:1], 11, v[0:1]
	v_or_b32_e32 v7, v0, v40
	v_or_b32_e32 v0, 0x600, v7
	v_lshl_add_u64 v[2:3], s[10:11], 0, v[0:1]
	s_nop 0
	v_mov_b32_e32 v3, v1
	v_lshl_add_u64 v[0:1], s[12:13], 0, v[0:1]
	v_lshlrev_b32_e32 v16, 16, v108
	v_or_b32_e32 v2, 0x640, v7
	v_lshl_add_u64 v[8:9], s[10:11], 0, v[2:3]
	s_nop 0
	v_mul_f32_e32 v8, 0xbfb8aa3b, v16
	v_exp_f32_e32 v8, v8
	v_lshlrev_b32_e32 v7, 16, v109
	v_add_f32_e32 v8, 1.0, v8
	v_div_scale_f32 v9, s[6:7], v8, v8, v16
	v_rcp_f32_e32 v17, v9
	s_nop 0
	v_fma_f32 v18, -v9, v17, 1.0
	v_fmac_f32_e32 v17, v18, v17
	v_div_scale_f32 v18, vcc, v16, v8, v16
	v_mul_f32_e32 v19, v18, v17
	v_fma_f32 v20, -v9, v19, v18
	v_fmac_f32_e32 v19, v20, v17
	v_fma_f32 v9, -v9, v19, v18
	v_div_fmas_f32 v9, v9, v17, v19
	v_div_fixup_f32 v8, v9, v8, v16
	v_mul_f32_e32 v9, 0xbfb8aa3b, v7
	v_exp_f32_e32 v9, v9
	v_mul_f32_e32 v5, v5, v8
	v_mul_f32_e32 v5, v6, v5
	v_mul_f32_e32 v5, v39, v5
	v_add_f32_e32 v9, 1.0, v9
	v_div_scale_f32 v16, s[6:7], v9, v9, v7
	v_rcp_f32_e32 v17, v16
	v_cvt_pk_bf16_f32 v5, v5, s0
	global_store_short v[0:1], v5, off
; __device__ __forceinline__ unsigned pk2(float lo, float hi) { return pg8::pk_bf16_rne(lo, hi); }
; __device__ __forceinline__ float bf2f(unsigned short u) { return __uint_as_float(((unsigned)u) << 16); }
; __device__ __forceinline__ float half_sum(float v) { v = row16_allsum(v); v = rows_pair_sum(v); return v; }
; __device__ __forceinline__ int crow(int r, int hi) { return (r & 3) + 8 * (r >> 2) + 4 * hi; }
; __device__ __forceinline__ void ret_out(const Params& P, int l, unsigned char* lds, int u, int tid) {
;     ...
;     for (int r = 0; r < 16; ++r) {
;         const float mean = half_sum(o0[r] + o1[r]) * (1.0f / 64.0f);
;         const float d0 = o0[r] - mean, d1 = o1[r] - mean;
;         const float var = half_sum(d0 * d0 + d1 * d1) * (1.0f / 64.0f);
;         const float rstd = 1.0f / sqrtf(var + 1e-5f);
;         const size_t t = tc + c0f + crow(r, hi);
;         const float ga = bf2f(ZR[t * 1024 + 768 + h * 64 + r32]), gb = bf2f(ZR[t * 1024 + 768 + h * 64 + 32 + r32]);
;         const float sa = ga / (1.0f + __expf(-ga)), sb = gb / (1.0f + __expf(-gb));
;         MIX[t * 1024 + 768 + h * 64 + r32] = (bf16_t)(pk2(sa * d0 * rstd * g0, 0.f) & 0xffffu);
;         MIX[t * 1024 + 768 + h * 64 + 32 + r32] = (bf16_t)(pk2(sb * d1 * rstd * g1, 0.f) & 0xffffu);
	v_fma_f32 v18, -v16, v17, 1.0
	v_fmac_f32_e32 v17, v18, v17
	v_div_scale_f32 v18, vcc, v7, v9, v7
	v_mul_f32_e32 v19, v18, v17
	v_fma_f32 v20, -v16, v19, v18
	v_fmac_f32_e32 v19, v20, v17
	v_fma_f32 v16, -v16, v19, v18
	v_div_fmas_f32 v16, v16, v17, v19
	v_div_fixup_f32 v7, v16, v9, v7
	v_mul_f32_e32 v0, v4, v7
	v_mul_f32_e32 v0, v6, v0
	v_mul_f32_e32 v0, v38, v0
	v_cvt_pk_bf16_f32 v4, v0, s0
	v_lshl_add_u64 v[0:1], s[12:13], 0, v[2:3]
	global_store_short v[0:1], v4, off
	v_add_f32_e32 v0, v10, v26
	s_nop 1
	v_add_f32_dpp v0, v0, v0 row_ror:8 row_mask:0xf bank_mask:0xf bound_ctrl:1
	s_nop 1
	v_add_f32_dpp v0, v0, v0 row_ror:4 row_mask:0xf bank_mask:0xf bound_ctrl:1
	s_nop 1
	v_add_f32_dpp v0, v0, v0 row_ror:2 row_mask:0xf bank_mask:0xf bound_ctrl:1
	s_nop 1
	v_add_f32_dpp v0, v0, v0 row_ror:1 row_mask:0xf bank_mask:0xf bound_ctrl:1
	v_mov_b32_e32 v1, v0
	s_nop 1
	v_permlane16_swap_b32_e32 v0, v1
	v_add_f32_e32 v0, v0, v1
	v_fmamk_f32 v4, v0, 0xbc800000, v26
	v_fmamk_f32 v5, v0, 0xbc800000, v10
	v_mul_f32_e32 v0, v4, v4
	v_fmac_f32_e32 v0, v5, v5
	s_nop 1
	v_add_f32_dpp v0, v0, v0 row_ror:8 row_mask:0xf bank_mask:0xf bound_ctrl:1
	s_nop 1
	v_add_f32_dpp v0, v0, v0 row_ror:4 row_mask:0xf bank_mask:0xf bound_ctrl:1
	s_nop 1
	v_add_f32_dpp v0, v0, v0 row_ror:2 row_mask:0xf bank_mask:0xf bound_ctrl:1
	s_nop 1
	v_add_f32_dpp v0, v0, v0 row_ror:1 row_mask:0xf bank_mask:0xf bound_ctrl:1
	v_mov_b32_e32 v1, v0
	s_nop 1
	v_permlane16_swap_b32_e32 v0, v1
	v_add_f32_e32 v0, v0, v1
	v_fmamk_f32 v0, v0, 0x3c800000, v200
	v_cmp_gt_f32_e32 vcc, s43, v0
	v_mul_f32_e32 v1, 0x4f800000, v0
	s_nop 0
	v_cndmask_b32_e32 v0, v0, v1, vcc
	v_sqrt_f32_e32 v1, v0
	s_nop 0
	v_add_u32_e32 v2, -1, v1
	v_fma_f32 v3, -v2, v1, v0
	v_cmp_ge_f32_e64 s[6:7], 0, v3
	v_add_u32_e32 v3, 1, v1
	s_nop 0
	v_cndmask_b32_e64 v2, v1, v2, s[6:7]
	v_fma_f32 v1, -v3, v1, v0
	v_cmp_lt_f32_e64 s[6:7], 0, v1
	s_nop 1
	v_cndmask_b32_e64 v1, v2, v3, s[6:7]
	v_mul_f32_e32 v2, 0x37800000, v1
	v_cndmask_b32_e32 v1, v1, v2, vcc
	v_cmp_class_f32_e32 vcc, v0, v175
	s_nop 1
	v_cndmask_b32_e32 v0, v1, v0, vcc
	v_div_scale_f32 v1, s[6:7], v0, v0, 1.0
	v_rcp_f32_e32 v2, v1
	s_nop 0
	v_fma_f32 v3, -v1, v2, 1.0
	v_fmac_f32_e32 v2, v3, v2
	v_div_scale_f32 v3, vcc, 1.0, v0, 1.0
	v_mul_f32_e32 v6, v3, v2
	v_fma_f32 v7, -v1, v6, v3
	v_fmac_f32_e32 v6, v7, v2
	v_fma_f32 v1, -v1, v6, v3
	v_div_fmas_f32 v1, v1, v2, v6
	v_div_fixup_f32 v6, v1, v0, 1.0
	v_or_b32_e32 v0, 18, v152
	v_mov_b32_e32 v1, v153
	v_lshl_add_u64 v[0:1], v[32:33], 0, v[0:1]
	v_lshlrev_b64 v[0:1], 11, v[0:1]
	v_or_b32_e32 v7, v0, v40
	v_or_b32_e32 v0, 0x600, v7
	v_lshl_add_u64 v[2:3], s[10:11], 0, v[0:1]
	s_nop 0
	v_mov_b32_e32 v3, v1
	v_lshl_add_u64 v[0:1], s[12:13], 0, v[0:1]
	v_lshlrev_b32_e32 v10, 16, v110
	v_or_b32_e32 v2, 0x640, v7
	v_lshl_add_u64 v[8:9], s[10:11], 0, v[2:3]
	s_nop 0
	v_mul_f32_e32 v8, 0xbfb8aa3b, v10
	v_exp_f32_e32 v8, v8
	v_lshlrev_b32_e32 v7, 16, v111
	v_add_f32_e32 v8, 1.0, v8
	v_div_scale_f32 v9, s[6:7], v8, v8, v10
	v_rcp_f32_e32 v16, v9
	s_nop 0
	v_fma_f32 v17, -v9, v16, 1.0
	v_fmac_f32_e32 v16, v17, v16
	v_div_scale_f32 v17, vcc, v10, v8, v10
	v_mul_f32_e32 v18, v17, v16
	v_fma_f32 v19, -v9, v18, v17
	v_fmac_f32_e32 v18, v19, v16
	v_fma_f32 v9, -v9, v18, v17
	v_div_fmas_f32 v9, v9, v16, v18
	v_div_fixup_f32 v8, v9, v8, v10
	v_mul_f32_e32 v9, 0xbfb8aa3b, v7
	v_exp_f32_e32 v9, v9
	v_mul_f32_e32 v5, v5, v8
	v_mul_f32_e32 v5, v6, v5
	v_mul_f32_e32 v5, v39, v5
	v_add_f32_e32 v9, 1.0, v9
	v_div_scale_f32 v10, s[6:7], v9, v9, v7
	v_rcp_f32_e32 v16, v10
	v_cvt_pk_bf16_f32 v5, v5, s0
	global_store_short v[0:1], v5, off
	v_fma_f32 v17, -v10, v16, 1.0
	v_fmac_f32_e32 v16, v17, v16
	v_div_scale_f32 v17, vcc, v7, v9, v7
	v_mul_f32_e32 v18, v17, v16
	v_fma_f32 v19, -v10, v18, v17
	v_fmac_f32_e32 v18, v19, v16
	v_fma_f32 v10, -v10, v18, v17
	v_div_fmas_f32 v10, v10, v16, v18
	v_div_fixup_f32 v7, v10, v9, v7
	v_mul_f32_e32 v0, v4, v7
	v_mul_f32_e32 v0, v6, v0
	v_mul_f32_e32 v0, v38, v0
	v_cvt_pk_bf16_f32 v4, v0, s0
	v_lshl_add_u64 v[0:1], s[12:13], 0, v[2:3]
	global_store_short v[0:1], v4, off
	v_add_f32_e32 v0, v11, v27
	s_nop 1
	v_add_f32_dpp v0, v0, v0 row_ror:8 row_mask:0xf bank_mask:0xf bound_ctrl:1
	s_nop 1
	v_add_f32_dpp v0, v0, v0 row_ror:4 row_mask:0xf bank_mask:0xf bound_ctrl:1
	s_nop 1
	v_add_f32_dpp v0, v0, v0 row_ror:2 row_mask:0xf bank_mask:0xf bound_ctrl:1
	s_nop 1
	v_add_f32_dpp v0, v0, v0 row_ror:1 row_mask:0xf bank_mask:0xf bound_ctrl:1
	v_mov_b32_e32 v1, v0
	s_nop 1
	v_permlane16_swap_b32_e32 v0, v1
	v_add_f32_e32 v0, v0, v1
	v_fmamk_f32 v4, v0, 0xbc800000, v27
	v_fmamk_f32 v5, v0, 0xbc800000, v11
	v_mul_f32_e32 v0, v4, v4
	v_fmac_f32_e32 v0, v5, v5
	s_nop 1
	v_add_f32_dpp v0, v0, v0 row_ror:8 row_mask:0xf bank_mask:0xf bound_ctrl:1
	s_nop 1
	v_add_f32_dpp v0, v0, v0 row_ror:4 row_mask:0xf bank_mask:0xf bound_ctrl:1
	s_nop 1
	v_add_f32_dpp v0, v0, v0 row_ror:2 row_mask:0xf bank_mask:0xf bound_ctrl:1
	s_nop 1
	v_add_f32_dpp v0, v0, v0 row_ror:1 row_mask:0xf bank_mask:0xf bound_ctrl:1
	v_mov_b32_e32 v1, v0
	s_nop 1
	v_permlane16_swap_b32_e32 v0, v1
	v_add_f32_e32 v0, v0, v1
	v_fmamk_f32 v0, v0, 0x3c800000, v200
	v_cmp_gt_f32_e32 vcc, s43, v0
	v_mul_f32_e32 v1, 0x4f800000, v0
	s_nop 0
	v_cndmask_b32_e32 v0, v0, v1, vcc
	v_sqrt_f32_e32 v1, v0
	s_nop 0
	v_add_u32_e32 v2, -1, v1
	v_fma_f32 v3, -v2, v1, v0
	v_cmp_ge_f32_e64 s[6:7], 0, v3
	v_add_u32_e32 v3, 1, v1
	s_nop 0
	v_cndmask_b32_e64 v2, v1, v2, s[6:7]
	v_fma_f32 v1, -v3, v1, v0
	v_cmp_lt_f32_e64 s[6:7], 0, v1
	s_nop 1
	v_cndmask_b32_e64 v1, v2, v3, s[6:7]
	v_mul_f32_e32 v2, 0x37800000, v1
	v_cndmask_b32_e32 v1, v1, v2, vcc
	v_cmp_class_f32_e32 vcc, v0, v175
; __device__ __forceinline__ unsigned pk2(float lo, float hi) { return pg8::pk_bf16_rne(lo, hi); }
; __device__ __forceinline__ float bf2f(unsigned short u) { return __uint_as_float(((unsigned)u) << 16); }
; __device__ __forceinline__ float half_sum(float v) { v = row16_allsum(v); v = rows_pair_sum(v); return v; }
; __device__ __forceinline__ int crow(int r, int hi) { return (r & 3) + 8 * (r >> 2) + 4 * hi; }
; __device__ __forceinline__ void ret_out(const Params& P, int l, unsigned char* lds, int u, int tid) {
;     ...
;     for (int r = 0; r < 16; ++r) {
;         const float mean = half_sum(o0[r] + o1[r]) * (1.0f / 64.0f);
;         const float d0 = o0[r] - mean, d1 = o1[r] - mean;
;         const float var = half_sum(d0 * d0 + d1 * d1) * (1.0f / 64.0f);
;         const float rstd = 1.0f / sqrtf(var + 1e-5f);
;         const size_t t = tc + c0f + crow(r, hi);
;         const float ga = bf2f(ZR[t * 1024 + 768 + h * 64 + r32]), gb = bf2f(ZR[t * 1024 + 768 + h * 64 + 32 + r32]);
;         const float sa = ga / (1.0f + __expf(-ga)), sb = gb / (1.0f + __expf(-gb));
;         MIX[t * 1024 + 768 + h * 64 + r32] = (bf16_t)(pk2(sa * d0 * rstd * g0, 0.f) & 0xffffu);
;         MIX[t * 1024 + 768 + h * 64 + 32 + r32] = (bf16_t)(pk2(sb * d1 * rstd * g1, 0.f) & 0xffffu);
	s_nop 1
	v_cndmask_b32_e32 v0, v1, v0, vcc
	v_div_scale_f32 v1, s[6:7], v0, v0, 1.0
	v_rcp_f32_e32 v2, v1
	s_nop 0
	v_fma_f32 v3, -v1, v2, 1.0
	v_fmac_f32_e32 v2, v3, v2
	v_div_scale_f32 v3, vcc, 1.0, v0, 1.0
	v_mul_f32_e32 v6, v3, v2
	v_fma_f32 v7, -v1, v6, v3
	v_fmac_f32_e32 v6, v7, v2
	v_fma_f32 v1, -v1, v6, v3
	v_div_fmas_f32 v1, v1, v2, v6
	v_div_fixup_f32 v6, v1, v0, 1.0
	v_or_b32_e32 v0, 19, v152
	v_mov_b32_e32 v1, v153
	v_lshl_add_u64 v[0:1], v[32:33], 0, v[0:1]
	v_lshlrev_b64 v[0:1], 11, v[0:1]
	v_or_b32_e32 v7, v0, v40
	v_or_b32_e32 v0, 0x600, v7
	v_lshl_add_u64 v[2:3], s[10:11], 0, v[0:1]
	s_nop 0
	v_mov_b32_e32 v3, v1
	v_lshl_add_u64 v[0:1], s[12:13], 0, v[0:1]
	v_lshlrev_b32_e32 v10, 16, v112
	v_or_b32_e32 v2, 0x640, v7
	v_lshl_add_u64 v[8:9], s[10:11], 0, v[2:3]
	s_nop 0
	v_mul_f32_e32 v8, 0xbfb8aa3b, v10
	v_exp_f32_e32 v8, v8
	v_lshlrev_b32_e32 v7, 16, v113
	v_add_f32_e32 v8, 1.0, v8
	v_div_scale_f32 v9, s[6:7], v8, v8, v10
	v_rcp_f32_e32 v11, v9
	s_nop 0
	v_fma_f32 v16, -v9, v11, 1.0
	v_fmac_f32_e32 v11, v16, v11
	v_div_scale_f32 v16, vcc, v10, v8, v10
	v_mul_f32_e32 v17, v16, v11
	v_fma_f32 v18, -v9, v17, v16
	v_fmac_f32_e32 v17, v18, v11
	v_fma_f32 v9, -v9, v17, v16
	v_div_fmas_f32 v9, v9, v11, v17
	v_div_fixup_f32 v8, v9, v8, v10
	v_mul_f32_e32 v9, 0xbfb8aa3b, v7
	v_exp_f32_e32 v9, v9
	v_mul_f32_e32 v5, v5, v8
	v_mul_f32_e32 v5, v6, v5
	v_mul_f32_e32 v5, v39, v5
	v_add_f32_e32 v9, 1.0, v9
	v_div_scale_f32 v10, s[6:7], v9, v9, v7
	v_rcp_f32_e32 v11, v10
	v_cvt_pk_bf16_f32 v5, v5, s0
	global_store_short v[0:1], v5, off
	v_fma_f32 v16, -v10, v11, 1.0
	v_fmac_f32_e32 v11, v16, v11
	v_div_scale_f32 v16, vcc, v7, v9, v7
	v_mul_f32_e32 v17, v16, v11
	v_fma_f32 v18, -v10, v17, v16
	v_fmac_f32_e32 v17, v18, v11
	v_fma_f32 v10, -v10, v17, v16
	v_div_fmas_f32 v10, v10, v11, v17
	v_div_fixup_f32 v7, v10, v9, v7
	v_mul_f32_e32 v0, v4, v7
	v_mul_f32_e32 v0, v6, v0
	v_mul_f32_e32 v0, v38, v0
	v_cvt_pk_bf16_f32 v4, v0, s0
	v_lshl_add_u64 v[0:1], s[12:13], 0, v[2:3]
	global_store_short v[0:1], v4, off
	v_add_f32_e32 v0, v12, v28
	s_nop 1
	v_add_f32_dpp v0, v0, v0 row_ror:8 row_mask:0xf bank_mask:0xf bound_ctrl:1
	s_nop 1
	v_add_f32_dpp v0, v0, v0 row_ror:4 row_mask:0xf bank_mask:0xf bound_ctrl:1
	s_nop 1
	v_add_f32_dpp v0, v0, v0 row_ror:2 row_mask:0xf bank_mask:0xf bound_ctrl:1
	s_nop 1
	v_add_f32_dpp v0, v0, v0 row_ror:1 row_mask:0xf bank_mask:0xf bound_ctrl:1
	v_mov_b32_e32 v1, v0
	s_nop 1
	v_permlane16_swap_b32_e32 v0, v1
	v_add_f32_e32 v0, v0, v1
	v_fmamk_f32 v4, v0, 0xbc800000, v28
	v_fmamk_f32 v5, v0, 0xbc800000, v12
	v_mul_f32_e32 v0, v4, v4
	v_fmac_f32_e32 v0, v5, v5
	s_nop 1
	v_add_f32_dpp v0, v0, v0 row_ror:8 row_mask:0xf bank_mask:0xf bound_ctrl:1
	s_nop 1
	v_add_f32_dpp v0, v0, v0 row_ror:4 row_mask:0xf bank_mask:0xf bound_ctrl:1
	s_nop 1
	v_add_f32_dpp v0, v0, v0 row_ror:2 row_mask:0xf bank_mask:0xf bound_ctrl:1
	s_nop 1
	v_add_f32_dpp v0, v0, v0 row_ror:1 row_mask:0xf bank_mask:0xf bound_ctrl:1
	v_mov_b32_e32 v1, v0
	s_nop 1
	v_permlane16_swap_b32_e32 v0, v1
	v_add_f32_e32 v0, v0, v1
	v_fmamk_f32 v0, v0, 0x3c800000, v200
	v_cmp_gt_f32_e32 vcc, s43, v0
	v_mul_f32_e32 v1, 0x4f800000, v0
	s_nop 0
	v_cndmask_b32_e32 v0, v0, v1, vcc
	v_sqrt_f32_e32 v1, v0
	s_nop 0
	v_add_u32_e32 v2, -1, v1
	v_fma_f32 v3, -v2, v1, v0
	v_cmp_ge_f32_e64 s[6:7], 0, v3
	v_add_u32_e32 v3, 1, v1
	s_nop 0
	v_cndmask_b32_e64 v2, v1, v2, s[6:7]
	v_fma_f32 v1, -v3, v1, v0
	v_cmp_lt_f32_e64 s[6:7], 0, v1
	s_nop 1
	v_cndmask_b32_e64 v1, v2, v3, s[6:7]
	v_mul_f32_e32 v2, 0x37800000, v1
	v_cndmask_b32_e32 v1, v1, v2, vcc
	v_cmp_class_f32_e32 vcc, v0, v175
	s_nop 1
	v_cndmask_b32_e32 v0, v1, v0, vcc
	v_div_scale_f32 v1, s[6:7], v0, v0, 1.0
	v_rcp_f32_e32 v2, v1
	s_nop 0
	v_fma_f32 v3, -v1, v2, 1.0
	v_fmac_f32_e32 v2, v3, v2
	v_div_scale_f32 v3, vcc, 1.0, v0, 1.0
	v_mul_f32_e32 v6, v3, v2
	v_fma_f32 v7, -v1, v6, v3
	v_fmac_f32_e32 v6, v7, v2
	v_fma_f32 v1, -v1, v6, v3
	v_div_fmas_f32 v1, v1, v2, v6
	v_div_fixup_f32 v6, v1, v0, 1.0
	v_or_b32_e32 v0, 24, v152
	v_mov_b32_e32 v1, v153
	v_lshl_add_u64 v[0:1], v[32:33], 0, v[0:1]
	v_lshlrev_b64 v[0:1], 11, v[0:1]
	v_or_b32_e32 v7, v0, v40
	v_or_b32_e32 v0, 0x600, v7
	v_lshl_add_u64 v[2:3], s[10:11], 0, v[0:1]
	s_nop 0
	v_mov_b32_e32 v3, v1
	v_lshl_add_u64 v[0:1], s[12:13], 0, v[0:1]
	v_lshlrev_b32_e32 v10, 16, v114
	v_or_b32_e32 v2, 0x640, v7
	v_lshl_add_u64 v[8:9], s[10:11], 0, v[2:3]
	s_nop 0
	v_mul_f32_e32 v8, 0xbfb8aa3b, v10
	v_exp_f32_e32 v8, v8
	v_lshlrev_b32_e32 v7, 16, v115
	v_add_f32_e32 v8, 1.0, v8
	v_div_scale_f32 v9, s[6:7], v8, v8, v10
	v_rcp_f32_e32 v11, v9
	s_nop 0
	v_fma_f32 v12, -v9, v11, 1.0
	v_fmac_f32_e32 v11, v12, v11
	v_div_scale_f32 v12, vcc, v10, v8, v10
	v_mul_f32_e32 v16, v12, v11
	v_fma_f32 v17, -v9, v16, v12
	v_fmac_f32_e32 v16, v17, v11
	v_fma_f32 v9, -v9, v16, v12
	v_div_fmas_f32 v9, v9, v11, v16
	v_div_fixup_f32 v8, v9, v8, v10
	v_mul_f32_e32 v9, 0xbfb8aa3b, v7
	v_exp_f32_e32 v9, v9
	v_mul_f32_e32 v5, v5, v8
	v_mul_f32_e32 v5, v6, v5
	v_mul_f32_e32 v5, v39, v5
	v_add_f32_e32 v9, 1.0, v9
	v_div_scale_f32 v10, s[6:7], v9, v9, v7
	v_rcp_f32_e32 v11, v10
	v_cvt_pk_bf16_f32 v5, v5, s0
	global_store_short v[0:1], v5, off
	v_fma_f32 v12, -v10, v11, 1.0
	v_fmac_f32_e32 v11, v12, v11
	v_div_scale_f32 v12, vcc, v7, v9, v7
	v_mul_f32_e32 v16, v12, v11
	v_fma_f32 v17, -v10, v16, v12
	v_fmac_f32_e32 v16, v17, v11
	v_fma_f32 v10, -v10, v16, v12
	v_div_fmas_f32 v10, v10, v11, v16
	v_div_fixup_f32 v7, v10, v9, v7
	v_mul_f32_e32 v0, v4, v7
	v_mul_f32_e32 v0, v6, v0
	v_mul_f32_e32 v0, v38, v0
	v_cvt_pk_bf16_f32 v4, v0, s0
	v_lshl_add_u64 v[0:1], s[12:13], 0, v[2:3]
	global_store_short v[0:1], v4, off
; __device__ __forceinline__ unsigned pk2(float lo, float hi) { return pg8::pk_bf16_rne(lo, hi); }
; __device__ __forceinline__ float bf2f(unsigned short u) { return __uint_as_float(((unsigned)u) << 16); }
; __device__ __forceinline__ float half_sum(float v) { v = row16_allsum(v); v = rows_pair_sum(v); return v; }
; __device__ __forceinline__ int crow(int r, int hi) { return (r & 3) + 8 * (r >> 2) + 4 * hi; }
; __device__ __forceinline__ void ret_out(const Params& P, int l, unsigned char* lds, int u, int tid) {
;     ...
;     for (int r = 0; r < 16; ++r) {
;         const float mean = half_sum(o0[r] + o1[r]) * (1.0f / 64.0f);
;         const float d0 = o0[r] - mean, d1 = o1[r] - mean;
;         const float var = half_sum(d0 * d0 + d1 * d1) * (1.0f / 64.0f);
;         const float rstd = 1.0f / sqrtf(var + 1e-5f);
;         const size_t t = tc + c0f + crow(r, hi);
;         const float ga = bf2f(ZR[t * 1024 + 768 + h * 64 + r32]), gb = bf2f(ZR[t * 1024 + 768 + h * 64 + 32 + r32]);
;         const float sa = ga / (1.0f + __expf(-ga)), sb = gb / (1.0f + __expf(-gb));
;         MIX[t * 1024 + 768 + h * 64 + r32] = (bf16_t)(pk2(sa * d0 * rstd * g0, 0.f) & 0xffffu);
;         MIX[t * 1024 + 768 + h * 64 + 32 + r32] = (bf16_t)(pk2(sb * d1 * rstd * g1, 0.f) & 0xffffu);
	v_add_f32_e32 v0, v13, v29
	s_nop 1
	v_add_f32_dpp v0, v0, v0 row_ror:8 row_mask:0xf bank_mask:0xf bound_ctrl:1
	s_nop 1
	v_add_f32_dpp v0, v0, v0 row_ror:4 row_mask:0xf bank_mask:0xf bound_ctrl:1
	s_nop 1
	v_add_f32_dpp v0, v0, v0 row_ror:2 row_mask:0xf bank_mask:0xf bound_ctrl:1
	s_nop 1
	v_add_f32_dpp v0, v0, v0 row_ror:1 row_mask:0xf bank_mask:0xf bound_ctrl:1
	v_mov_b32_e32 v1, v0
	s_nop 1
	v_permlane16_swap_b32_e32 v0, v1
	v_add_f32_e32 v0, v0, v1
	v_fmamk_f32 v4, v0, 0xbc800000, v29
	v_fmamk_f32 v5, v0, 0xbc800000, v13
	v_mul_f32_e32 v0, v4, v4
	v_fmac_f32_e32 v0, v5, v5
	s_nop 1
	v_add_f32_dpp v0, v0, v0 row_ror:8 row_mask:0xf bank_mask:0xf bound_ctrl:1
	s_nop 1
	v_add_f32_dpp v0, v0, v0 row_ror:4 row_mask:0xf bank_mask:0xf bound_ctrl:1
	s_nop 1
	v_add_f32_dpp v0, v0, v0 row_ror:2 row_mask:0xf bank_mask:0xf bound_ctrl:1
	s_nop 1
	v_add_f32_dpp v0, v0, v0 row_ror:1 row_mask:0xf bank_mask:0xf bound_ctrl:1
	v_mov_b32_e32 v1, v0
	s_nop 1
	v_permlane16_swap_b32_e32 v0, v1
	v_add_f32_e32 v0, v0, v1
	v_fmamk_f32 v0, v0, 0x3c800000, v200
	v_cmp_gt_f32_e32 vcc, s43, v0
	v_mul_f32_e32 v1, 0x4f800000, v0
	s_nop 0
	v_cndmask_b32_e32 v0, v0, v1, vcc
	v_sqrt_f32_e32 v1, v0
	s_nop 0
	v_add_u32_e32 v2, -1, v1
	v_fma_f32 v3, -v2, v1, v0
	v_cmp_ge_f32_e64 s[6:7], 0, v3
	v_add_u32_e32 v3, 1, v1
	s_nop 0
	v_cndmask_b32_e64 v2, v1, v2, s[6:7]
	v_fma_f32 v1, -v3, v1, v0
	v_cmp_lt_f32_e64 s[6:7], 0, v1
	s_nop 1
	v_cndmask_b32_e64 v1, v2, v3, s[6:7]
	v_mul_f32_e32 v2, 0x37800000, v1
	v_cndmask_b32_e32 v1, v1, v2, vcc
	v_cmp_class_f32_e32 vcc, v0, v175
	s_nop 1
	v_cndmask_b32_e32 v0, v1, v0, vcc
	v_div_scale_f32 v1, s[6:7], v0, v0, 1.0
	v_rcp_f32_e32 v2, v1
	s_nop 0
	v_fma_f32 v3, -v1, v2, 1.0
	v_fmac_f32_e32 v2, v3, v2
	v_div_scale_f32 v3, vcc, 1.0, v0, 1.0
	v_mul_f32_e32 v6, v3, v2
	v_fma_f32 v7, -v1, v6, v3
	v_fmac_f32_e32 v6, v7, v2
	v_fma_f32 v1, -v1, v6, v3
	v_div_fmas_f32 v1, v1, v2, v6
	v_div_fixup_f32 v6, v1, v0, 1.0
	v_or_b32_e32 v0, 25, v152
	v_mov_b32_e32 v1, v153
	v_lshl_add_u64 v[0:1], v[32:33], 0, v[0:1]
	v_lshlrev_b64 v[0:1], 11, v[0:1]
	v_or_b32_e32 v7, v0, v40
	v_or_b32_e32 v0, 0x600, v7
	v_lshl_add_u64 v[2:3], s[10:11], 0, v[0:1]
	s_nop 0
	v_mov_b32_e32 v3, v1
	v_lshl_add_u64 v[0:1], s[12:13], 0, v[0:1]
	v_lshlrev_b32_e32 v10, 16, v116
	v_or_b32_e32 v2, 0x640, v7
	v_lshl_add_u64 v[8:9], s[10:11], 0, v[2:3]
	s_nop 0
	v_mul_f32_e32 v8, 0xbfb8aa3b, v10
	v_exp_f32_e32 v8, v8
	v_lshlrev_b32_e32 v7, 16, v117
	v_add_f32_e32 v8, 1.0, v8
	v_div_scale_f32 v9, s[6:7], v8, v8, v10
	v_rcp_f32_e32 v11, v9
	s_nop 0
	v_fma_f32 v12, -v9, v11, 1.0
	v_fmac_f32_e32 v11, v12, v11
	v_div_scale_f32 v12, vcc, v10, v8, v10
	v_mul_f32_e32 v13, v12, v11
	v_fma_f32 v16, -v9, v13, v12
	v_fmac_f32_e32 v13, v16, v11
	v_fma_f32 v9, -v9, v13, v12
	v_div_fmas_f32 v9, v9, v11, v13
	v_div_fixup_f32 v8, v9, v8, v10
	v_mul_f32_e32 v9, 0xbfb8aa3b, v7
	v_exp_f32_e32 v9, v9
	v_mul_f32_e32 v5, v5, v8
	v_mul_f32_e32 v5, v6, v5
	v_mul_f32_e32 v5, v39, v5
	v_add_f32_e32 v9, 1.0, v9
	v_div_scale_f32 v10, s[6:7], v9, v9, v7
	v_rcp_f32_e32 v11, v10
	v_cvt_pk_bf16_f32 v5, v5, s0
	global_store_short v[0:1], v5, off
	v_fma_f32 v12, -v10, v11, 1.0
	v_fmac_f32_e32 v11, v12, v11
	v_div_scale_f32 v12, vcc, v7, v9, v7
	v_mul_f32_e32 v13, v12, v11
	v_fma_f32 v16, -v10, v13, v12
	v_fmac_f32_e32 v13, v16, v11
	v_fma_f32 v10, -v10, v13, v12
	v_div_fmas_f32 v10, v10, v11, v13
	v_div_fixup_f32 v7, v10, v9, v7
	v_mul_f32_e32 v0, v4, v7
	v_mul_f32_e32 v0, v6, v0
	v_mul_f32_e32 v0, v38, v0
	v_cvt_pk_bf16_f32 v4, v0, s0
	v_lshl_add_u64 v[0:1], s[12:13], 0, v[2:3]
	global_store_short v[0:1], v4, off
	v_add_f32_e32 v0, v14, v30
	s_nop 1
	v_add_f32_dpp v0, v0, v0 row_ror:8 row_mask:0xf bank_mask:0xf bound_ctrl:1
	s_nop 1
	v_add_f32_dpp v0, v0, v0 row_ror:4 row_mask:0xf bank_mask:0xf bound_ctrl:1
	s_nop 1
	v_add_f32_dpp v0, v0, v0 row_ror:2 row_mask:0xf bank_mask:0xf bound_ctrl:1
	s_nop 1
	v_add_f32_dpp v0, v0, v0 row_ror:1 row_mask:0xf bank_mask:0xf bound_ctrl:1
	v_mov_b32_e32 v1, v0
	s_nop 1
	v_permlane16_swap_b32_e32 v0, v1
	v_add_f32_e32 v0, v0, v1
	v_fmamk_f32 v4, v0, 0xbc800000, v30
	v_fmamk_f32 v5, v0, 0xbc800000, v14
	v_mul_f32_e32 v0, v4, v4
	v_fmac_f32_e32 v0, v5, v5
	s_nop 1
	v_add_f32_dpp v0, v0, v0 row_ror:8 row_mask:0xf bank_mask:0xf bound_ctrl:1
	s_nop 1
	v_add_f32_dpp v0, v0, v0 row_ror:4 row_mask:0xf bank_mask:0xf bound_ctrl:1
	s_nop 1
	v_add_f32_dpp v0, v0, v0 row_ror:2 row_mask:0xf bank_mask:0xf bound_ctrl:1
	s_nop 1
	v_add_f32_dpp v0, v0, v0 row_ror:1 row_mask:0xf bank_mask:0xf bound_ctrl:1
	v_mov_b32_e32 v1, v0
	s_nop 1
	v_permlane16_swap_b32_e32 v0, v1
	v_add_f32_e32 v0, v0, v1
	v_fmamk_f32 v0, v0, 0x3c800000, v200
	v_cmp_gt_f32_e32 vcc, s43, v0
	v_mul_f32_e32 v1, 0x4f800000, v0
	s_nop 0
	v_cndmask_b32_e32 v0, v0, v1, vcc
	v_sqrt_f32_e32 v1, v0
	s_nop 0
	v_add_u32_e32 v2, -1, v1
	v_fma_f32 v3, -v2, v1, v0
	v_cmp_ge_f32_e64 s[6:7], 0, v3
	v_add_u32_e32 v3, 1, v1
	s_nop 0
	v_cndmask_b32_e64 v2, v1, v2, s[6:7]
	v_fma_f32 v1, -v3, v1, v0
	v_cmp_lt_f32_e64 s[6:7], 0, v1
	s_nop 1
	v_cndmask_b32_e64 v1, v2, v3, s[6:7]
	v_mul_f32_e32 v2, 0x37800000, v1
	v_cndmask_b32_e32 v1, v1, v2, vcc
	v_cmp_class_f32_e32 vcc, v0, v175
	s_nop 1
	v_cndmask_b32_e32 v0, v1, v0, vcc
	v_div_scale_f32 v1, s[6:7], v0, v0, 1.0
	v_rcp_f32_e32 v2, v1
	s_nop 0
	v_fma_f32 v3, -v1, v2, 1.0
	v_fmac_f32_e32 v2, v3, v2
	v_div_scale_f32 v3, vcc, 1.0, v0, 1.0
; __device__ __forceinline__ unsigned pk2(float lo, float hi) { return pg8::pk_bf16_rne(lo, hi); }
; __device__ __forceinline__ float bf2f(unsigned short u) { return __uint_as_float(((unsigned)u) << 16); }
; __device__ __forceinline__ float half_sum(float v) { v = row16_allsum(v); v = rows_pair_sum(v); return v; }
; __device__ __forceinline__ int crow(int r, int hi) { return (r & 3) + 8 * (r >> 2) + 4 * hi; }
; __device__ __forceinline__ void ret_out(const Params& P, int l, unsigned char* lds, int u, int tid) {
;     ...
;     for (int r = 0; r < 16; ++r) {
;         const float mean = half_sum(o0[r] + o1[r]) * (1.0f / 64.0f);
;         const float d0 = o0[r] - mean, d1 = o1[r] - mean;
;         const float var = half_sum(d0 * d0 + d1 * d1) * (1.0f / 64.0f);
;         const float rstd = 1.0f / sqrtf(var + 1e-5f);
;         const size_t t = tc + c0f + crow(r, hi);
;         const float ga = bf2f(ZR[t * 1024 + 768 + h * 64 + r32]), gb = bf2f(ZR[t * 1024 + 768 + h * 64 + 32 + r32]);
;         const float sa = ga / (1.0f + __expf(-ga)), sb = gb / (1.0f + __expf(-gb));
;         MIX[t * 1024 + 768 + h * 64 + r32] = (bf16_t)(pk2(sa * d0 * rstd * g0, 0.f) & 0xffffu);
;         MIX[t * 1024 + 768 + h * 64 + 32 + r32] = (bf16_t)(pk2(sb * d1 * rstd * g1, 0.f) & 0xffffu);
;     }
;     __syncthreads();
	v_mul_f32_e32 v6, v3, v2
	v_fma_f32 v7, -v1, v6, v3
	v_fmac_f32_e32 v6, v7, v2
	v_fma_f32 v1, -v1, v6, v3
	v_div_fmas_f32 v1, v1, v2, v6
	v_div_fixup_f32 v6, v1, v0, 1.0
	v_or_b32_e32 v0, 26, v152
	v_mov_b32_e32 v1, v153
	v_lshl_add_u64 v[0:1], v[32:33], 0, v[0:1]
	v_lshlrev_b64 v[0:1], 11, v[0:1]
	v_or_b32_e32 v7, v0, v40
	v_or_b32_e32 v0, 0x600, v7
	v_lshl_add_u64 v[2:3], s[10:11], 0, v[0:1]
	s_nop 0
	v_mov_b32_e32 v3, v1
	v_lshl_add_u64 v[0:1], s[12:13], 0, v[0:1]
	v_or_b32_e32 v152, 27, v152
	v_lshlrev_b32_e32 v10, 16, v118
	v_or_b32_e32 v2, 0x640, v7
	v_lshl_add_u64 v[8:9], s[10:11], 0, v[2:3]
	s_nop 0
	v_mul_f32_e32 v8, 0xbfb8aa3b, v10
	v_exp_f32_e32 v8, v8
	v_lshlrev_b32_e32 v7, 16, v119
	v_add_f32_e32 v8, 1.0, v8
	v_div_scale_f32 v9, s[6:7], v8, v8, v10
	v_rcp_f32_e32 v11, v9
	s_nop 0
	v_fma_f32 v12, -v9, v11, 1.0
	v_fmac_f32_e32 v11, v12, v11
	v_div_scale_f32 v12, vcc, v10, v8, v10
	v_mul_f32_e32 v13, v12, v11
	v_fma_f32 v14, -v9, v13, v12
	v_fmac_f32_e32 v13, v14, v11
	v_fma_f32 v9, -v9, v13, v12
	v_div_fmas_f32 v9, v9, v11, v13
	v_div_fixup_f32 v8, v9, v8, v10
	v_mul_f32_e32 v9, 0xbfb8aa3b, v7
	v_exp_f32_e32 v9, v9
	v_mul_f32_e32 v5, v5, v8
	v_mul_f32_e32 v5, v6, v5
	v_mul_f32_e32 v5, v39, v5
	v_add_f32_e32 v9, 1.0, v9
	v_div_scale_f32 v10, s[6:7], v9, v9, v7
	v_rcp_f32_e32 v11, v10
	v_cvt_pk_bf16_f32 v5, v5, s0
	global_store_short v[0:1], v5, off
	v_fma_f32 v12, -v10, v11, 1.0
	v_fmac_f32_e32 v11, v12, v11
	v_div_scale_f32 v12, vcc, v7, v9, v7
	v_mul_f32_e32 v13, v12, v11
	v_fma_f32 v14, -v10, v13, v12
	v_fmac_f32_e32 v13, v14, v11
	v_fma_f32 v10, -v10, v13, v12
	v_div_fmas_f32 v10, v10, v11, v13
	v_div_fixup_f32 v7, v10, v9, v7
	v_mul_f32_e32 v0, v4, v7
	v_mul_f32_e32 v0, v6, v0
	v_mul_f32_e32 v0, v38, v0
	v_cvt_pk_bf16_f32 v4, v0, s0
	v_lshl_add_u64 v[0:1], s[12:13], 0, v[2:3]
	global_store_short v[0:1], v4, off
	v_add_f32_e32 v0, v15, v31
	s_nop 1
	v_add_f32_dpp v0, v0, v0 row_ror:8 row_mask:0xf bank_mask:0xf bound_ctrl:1
	s_nop 1
	v_add_f32_dpp v0, v0, v0 row_ror:4 row_mask:0xf bank_mask:0xf bound_ctrl:1
	s_nop 1
	v_add_f32_dpp v0, v0, v0 row_ror:2 row_mask:0xf bank_mask:0xf bound_ctrl:1
	s_nop 1
	v_add_f32_dpp v0, v0, v0 row_ror:1 row_mask:0xf bank_mask:0xf bound_ctrl:1
	v_mov_b32_e32 v1, v0
	s_nop 1
	v_permlane16_swap_b32_e32 v0, v1
	v_add_f32_e32 v0, v0, v1
	v_fmac_f32_e32 v31, 0xbc800000, v0
	v_fmac_f32_e32 v15, 0xbc800000, v0
	v_mul_f32_e32 v0, v31, v31
	v_fmac_f32_e32 v0, v15, v15
	s_nop 1
	v_add_f32_dpp v0, v0, v0 row_ror:8 row_mask:0xf bank_mask:0xf bound_ctrl:1
	s_nop 1
	v_add_f32_dpp v0, v0, v0 row_ror:4 row_mask:0xf bank_mask:0xf bound_ctrl:1
	s_nop 1
	v_add_f32_dpp v0, v0, v0 row_ror:2 row_mask:0xf bank_mask:0xf bound_ctrl:1
	s_nop 1
	v_add_f32_dpp v0, v0, v0 row_ror:1 row_mask:0xf bank_mask:0xf bound_ctrl:1
	v_mov_b32_e32 v1, v0
	s_nop 1
	v_permlane16_swap_b32_e32 v0, v1
	v_add_f32_e32 v0, v0, v1
	v_fmamk_f32 v0, v0, 0x3c800000, v200
	v_cmp_gt_f32_e32 vcc, s43, v0
	v_mul_f32_e32 v1, 0x4f800000, v0
	s_nop 0
	v_cndmask_b32_e32 v0, v0, v1, vcc
	v_sqrt_f32_e32 v1, v0
	s_nop 0
	v_add_u32_e32 v2, -1, v1
	v_fma_f32 v3, -v2, v1, v0
	v_cmp_ge_f32_e64 s[6:7], 0, v3
	v_add_u32_e32 v3, 1, v1
	s_nop 0
	v_cndmask_b32_e64 v2, v1, v2, s[6:7]
	v_fma_f32 v1, -v3, v1, v0
	v_cmp_lt_f32_e64 s[6:7], 0, v1
	s_nop 1
	v_cndmask_b32_e64 v1, v2, v3, s[6:7]
	v_mul_f32_e32 v2, 0x37800000, v1
	v_cndmask_b32_e32 v1, v1, v2, vcc
	v_cmp_class_f32_e32 vcc, v0, v175
	s_nop 1
	v_cndmask_b32_e32 v0, v1, v0, vcc
	v_div_scale_f32 v1, s[6:7], v0, v0, 1.0
	v_rcp_f32_e32 v2, v1
	s_nop 0
	v_fma_f32 v3, -v1, v2, 1.0
	v_fmac_f32_e32 v2, v3, v2
	v_div_scale_f32 v3, vcc, 1.0, v0, 1.0
	v_mul_f32_e32 v4, v3, v2
	v_fma_f32 v5, -v1, v4, v3
	v_fmac_f32_e32 v4, v5, v2
	v_fma_f32 v1, -v1, v4, v3
	v_div_fmas_f32 v1, v1, v2, v4
	v_div_fixup_f32 v4, v1, v0, 1.0
	v_lshl_add_u64 v[0:1], v[32:33], 0, v[152:153]
	v_lshlrev_b64 v[0:1], 11, v[0:1]
	v_or_b32_e32 v5, v0, v40
	v_or_b32_e32 v0, 0x600, v5
	v_lshl_add_u64 v[2:3], s[10:11], 0, v[0:1]
	s_nop 0
	v_mov_b32_e32 v3, v1
	v_lshl_add_u64 v[0:1], s[12:13], 0, v[0:1]
	v_lshlrev_b32_e32 v8, 16, v120
	v_or_b32_e32 v2, 0x640, v5
	v_lshl_add_u64 v[6:7], s[10:11], 0, v[2:3]
	s_nop 0
	v_mul_f32_e32 v6, 0xbfb8aa3b, v8
	v_exp_f32_e32 v6, v6
	v_lshlrev_b32_e32 v5, 16, v121
	v_add_f32_e32 v6, 1.0, v6
	v_div_scale_f32 v7, s[6:7], v6, v6, v8
	v_rcp_f32_e32 v9, v7
	s_nop 0
	v_fma_f32 v10, -v7, v9, 1.0
	v_fmac_f32_e32 v9, v10, v9
	v_div_scale_f32 v10, vcc, v8, v6, v8
	v_mul_f32_e32 v11, v10, v9
	v_fma_f32 v12, -v7, v11, v10
	v_fmac_f32_e32 v11, v12, v9
	v_fma_f32 v7, -v7, v11, v10
	v_div_fmas_f32 v7, v7, v9, v11
	v_div_fixup_f32 v6, v7, v6, v8
	v_mul_f32_e32 v7, 0xbfb8aa3b, v5
	v_exp_f32_e32 v7, v7
	v_mul_f32_e32 v6, v15, v6
	v_mul_f32_e32 v6, v4, v6
	v_mul_f32_e32 v6, v39, v6
	v_add_f32_e32 v7, 1.0, v7
	v_div_scale_f32 v8, s[6:7], v7, v7, v5
	v_rcp_f32_e32 v9, v8
	v_cvt_pk_bf16_f32 v6, v6, s0
	global_store_short v[0:1], v6, off
	v_fma_f32 v10, -v8, v9, 1.0
	v_fmac_f32_e32 v9, v10, v9
	v_div_scale_f32 v10, vcc, v5, v7, v5
	v_mul_f32_e32 v11, v10, v9
	v_fma_f32 v12, -v8, v11, v10
	v_fmac_f32_e32 v11, v12, v9
	v_fma_f32 v8, -v8, v11, v10
	v_div_fmas_f32 v8, v8, v9, v11
	v_div_fixup_f32 v5, v8, v7, v5
	v_mul_f32_e32 v0, v31, v5
	v_mul_f32_e32 v0, v4, v0
	v_mul_f32_e32 v0, v38, v0
	v_cvt_pk_bf16_f32 v4, v0, s0
	v_lshl_add_u64 v[0:1], s[12:13], 0, v[2:3]
	global_store_short v[0:1], v4, off
	s_barrier
